# nt hint also on the down-projection residual base loads and the pooling pass row loads
# baseline (speedup 1.0000x reference)
; #define GAS __attribute__((address_space(1)))
; __device__ __forceinline__ unsigned pk2(float lo, float hi) { f32x2_t v = {lo, hi}; bf16x2_t b = __builtin_convertvector(v, bf16x2_t); return __builtin_bit_cast(unsigned, b); }
; #define U_LD(p) ({ const v2u w_ = *(const v2u*)(p); (f32x4){bflo(w_.x), bfhi(w_.x), bflo(w_.y), bfhi(w_.y)}; })
; __device__ __forceinline__ void p3_pool(Frame& F) {
;     ...
;         if (tk2 >= 2 * (NPR / 32 + DBATCH)) break;
;         const int tk = tk2 >> 1, c0 = (tk2 & 1) * 256 + lane * 4, w = 2 << (c0 >> 7);
;         const bool isP = tk < NPR / 32;
;         const int b = isP ? (tk >> 6) : (tk - NPR / 32), s0 = isP ? ((tk & 63) << 5) : 0, nsteps = isP ? 47 : 23;
;         const size_t mbase = isP ? (size_t)b * SEQ : (size_t)NPR + (size_t)b * 8;
;         f32x4 S0 = (f32x4){0.f, 0.f, 0.f, 0.f};
; #pragma unroll 8
;         for (int i = 0; i < nsteps; ++i) {
;             const int s = s0 - 15 + i;
;             const int so = s - w;
;             f32x4 n0 = (f32x4){0.f, 0.f, 0.f, 0.f}, o0 = n0;
;             if (isP) {
;                 if (s >= 0) n0 = U_LD(U + (mbase + s) * 512 + c0);
;                 if (i >= w && so >= 0) o0 = U_LD(U + (mbase + so) * 512 + c0);
;             } else {
;                 if (s >= 0) n0 = U_LD(U + (mbase + s) * 512 + c0); else n0 = *(const f32x4*)(state_pool + ((size_t)b * 15 + (s + 15)) * 512 + c0);
;                 if (i >= w) { if (so >= 0) o0 = U_LD(U + (mbase + so) * 512 + c0); else o0 = *(const f32x4*)(state_pool + ((size_t)b * 15 + (so + 15)) * 512 + c0); }
;             }
;             S0 += n0 - o0;
;             if (i >= 15) {
;                 const int cnt = isP ? (w < s + 1 ? w : s + 1) : w; const float inv = 1.f / (float)cnt;
;                 const f32x4 d0 = S0 * inv - n0;
;                 v2u wv; wv.x = pk2(d0[0], d0[1]); wv.y = pk2(d0[2], d0[3]);
;                 *(GAS v2u*)(D + (size_t)(c0 >> 8) * ((size_t)MT * 256) + (mbase + s) * 256 + (c0 & 255)) = wv;
;             }
;             if (!isP && s >= -7 && s < 0) *(GAS f32x4*)(out + O_POOLS + ((size_t)b * 15 + (s + 7)) * 512 + c0) = n0;
.Lp3f_entry:
	s_and_b32 s82, s24, 1
	s_lshr_b32 s83, s24, 7
	s_and_b32 s84, s25, 63
	s_lshl_b32 s85, s83, 11
	s_lshl_b32 s86, s84, 5
	s_add_i32 s85, s85, s86
	v_lshlrev_b32_e32 v36, 1, v32
	s_movk_i32 s87, 0x80
	v_cmp_le_u32_e64 s[94:95], s87, v32
	s_lshl_b32 s87, s82, 9
	s_lshl_b32 s88, s85, 10
	s_add_u32 s88, s88, s87
	s_add_u32 s88, s12, s88
	s_addc_u32 s89, s13, 0
	s_mul_i32 s92, s82, 0x1080000
	s_lshl_b32 s93, s85, 9
	s_add_u32 s92, s92, s93
	s_add_u32 s92, s92, 0xb400000
	s_add_u32 s90, s12, s92
	s_addc_u32 s91, s13, 0
	s_cmp_eq_u32 s84, 0
	s_cbranch_scc1 .Lp3f_ld15
	s_sub_u32 s96, s88, 0x3c00
	s_subb_u32 s97, s89, 0
	global_load_dwordx2 v[40:41], v36, s[96:97] nt
	global_load_dwordx2 v[42:43], v36, s[96:97] offset:1024 nt
	global_load_dwordx2 v[44:45], v36, s[96:97] offset:2048 nt
	global_load_dwordx2 v[46:47], v36, s[96:97] offset:3072 nt
	s_add_u32 s96, s96, 0x1000
	s_addc_u32 s97, s97, 0
	global_load_dwordx2 v[48:49], v36, s[96:97] nt
	global_load_dwordx2 v[50:51], v36, s[96:97] offset:1024 nt
	global_load_dwordx2 v[52:53], v36, s[96:97] offset:2048 nt
	global_load_dwordx2 v[54:55], v36, s[96:97] offset:3072 nt
	s_add_u32 s96, s96, 0x1000
	s_addc_u32 s97, s97, 0
	global_load_dwordx2 v[56:57], v36, s[96:97] nt
	global_load_dwordx2 v[58:59], v36, s[96:97] offset:1024 nt
	global_load_dwordx2 v[60:61], v36, s[96:97] offset:2048 nt
	global_load_dwordx2 v[62:63], v36, s[96:97] offset:3072 nt
	s_add_u32 s96, s96, 0x1000
	s_addc_u32 s97, s97, 0
	global_load_dwordx2 v[64:65], v36, s[96:97] nt
	global_load_dwordx2 v[66:67], v36, s[96:97] offset:1024 nt
	global_load_dwordx2 v[68:69], v36, s[96:97] offset:2048 nt
.Lp3f_ld15:
	s_mov_b64 s[96:97], s[88:89]
	global_load_dwordx2 v[70:71], v36, s[96:97] nt
	global_load_dwordx2 v[72:73], v36, s[96:97] offset:1024 nt
	global_load_dwordx2 v[74:75], v36, s[96:97] offset:2048 nt
	global_load_dwordx2 v[76:77], v36, s[96:97] offset:3072 nt
	s_add_u32 s96, s96, 0x1000
	s_addc_u32 s97, s97, 0
	global_load_dwordx2 v[78:79], v36, s[96:97] nt
	global_load_dwordx2 v[80:81], v36, s[96:97] offset:1024 nt
	global_load_dwordx2 v[82:83], v36, s[96:97] offset:2048 nt
	global_load_dwordx2 v[84:85], v36, s[96:97] offset:3072 nt
	s_add_u32 s96, s96, 0x1000
	s_addc_u32 s97, s97, 0
	global_load_dwordx2 v[86:87], v36, s[96:97] nt
	global_load_dwordx2 v[88:89], v36, s[96:97] offset:1024 nt
	global_load_dwordx2 v[90:91], v36, s[96:97] offset:2048 nt
	global_load_dwordx2 v[92:93], v36, s[96:97] offset:3072 nt
	s_add_u32 s96, s96, 0x1000
	s_addc_u32 s97, s97, 0
	global_load_dwordx2 v[94:95], v36, s[96:97] nt
	global_load_dwordx2 v[96:97], v36, s[96:97] offset:1024 nt
	global_load_dwordx2 v[98:99], v36, s[96:97] offset:2048 nt
	global_load_dwordx2 v[100:101], v36, s[96:97] offset:3072 nt
	s_add_u32 s96, s96, 0x1000
	s_addc_u32 s97, s97, 0
	global_load_dwordx2 v[102:103], v36, s[96:97] nt
	global_load_dwordx2 v[104:105], v36, s[96:97] offset:1024 nt
	global_load_dwordx2 v[106:107], v36, s[96:97] offset:2048 nt
	global_load_dwordx2 v[108:109], v36, s[96:97] offset:3072 nt
	s_add_u32 s96, s96, 0x1000
	s_addc_u32 s97, s97, 0
	global_load_dwordx2 v[110:111], v36, s[96:97] nt
	global_load_dwordx2 v[112:113], v36, s[96:97] offset:1024 nt
	global_load_dwordx2 v[114:115], v36, s[96:97] offset:2048 nt
	global_load_dwordx2 v[116:117], v36, s[96:97] offset:3072 nt
	s_add_u32 s96, s96, 0x1000
	s_addc_u32 s97, s97, 0
	global_load_dwordx2 v[118:119], v36, s[96:97] nt
	global_load_dwordx2 v[120:121], v36, s[96:97] offset:1024 nt
	global_load_dwordx2 v[122:123], v36, s[96:97] offset:2048 nt
	global_load_dwordx2 v[124:125], v36, s[96:97] offset:3072 nt
	s_add_u32 s96, s96, 0x1000
	s_addc_u32 s97, s97, 0
	global_load_dwordx2 v[126:127], v36, s[96:97] nt
	global_load_dwordx2 v[128:129], v36, s[96:97] offset:1024 nt
	global_load_dwordx2 v[130:131], v36, s[96:97] offset:2048 nt
	global_load_dwordx2 v[132:133], v36, s[96:97] offset:3072 nt
	s_cmp_eq_u32 s84, 0
	s_cbranch_scc1 .Lp3f_first
	s_cmp_eq_u32 s82, 0
	s_cbranch_scc0 .Lp3f_n1
	v_mov_b32_e32 v140, 0
	v_mov_b32_e32 v141, 0
	v_mov_b32_e32 v142, 0
	v_mov_b32_e32 v143, 0
	v_mov_b32_e32 v166, 0
	v_mov_b32_e32 v167, 0
	v_mov_b32_e32 v168, 0x3f000000
	v_mov_b32_e32 v169, 0x3e800000
	v_cndmask_b32_e64 v164, v168, v169, s[94:95]
	s_mov_b64 s[96:97], s[90:91]
	s_waitcnt vmcnt(46)
	v_lshlrev_b32_e32 v144, 16, v40
	v_and_b32_e32 v145, 0xffff0000, v40
	v_lshlrev_b32_e32 v146, 16, v41
	v_and_b32_e32 v147, 0xffff0000, v41
	v_pk_add_f32 v[140:141], v[140:141], v[144:145]
	v_pk_add_f32 v[142:143], v[142:143], v[146:147]
	s_waitcnt vmcnt(45)
	v_lshlrev_b32_e32 v144, 16, v42
	v_and_b32_e32 v145, 0xffff0000, v42
	v_lshlrev_b32_e32 v146, 16, v43
	v_and_b32_e32 v147, 0xffff0000, v43
	v_pk_add_f32 v[140:141], v[140:141], v[144:145]
	v_pk_add_f32 v[142:143], v[142:143], v[146:147]
	s_waitcnt vmcnt(44)
	v_lshlrev_b32_e32 v144, 16, v44
	v_and_b32_e32 v145, 0xffff0000, v44
	v_lshlrev_b32_e32 v146, 16, v45
	v_and_b32_e32 v147, 0xffff0000, v45
	v_cndmask_b32_e64 v148, v40, v166, s[94:95]
	v_cndmask_b32_e64 v149, v41, v167, s[94:95]
	v_lshlrev_b32_e32 v150, 16, v148
	v_and_b32_e32 v151, 0xffff0000, v148
	v_lshlrev_b32_e32 v152, 16, v149
	v_and_b32_e32 v153, 0xffff0000, v149
	v_pk_add_f32 v[154:155], v[144:145], v[150:151] neg_lo:[0,1] neg_hi:[0,1]
	v_pk_add_f32 v[156:157], v[146:147], v[152:153] neg_lo:[0,1] neg_hi:[0,1]
	v_pk_add_f32 v[140:141], v[140:141], v[154:155]
	v_pk_add_f32 v[142:143], v[142:143], v[156:157]
	s_waitcnt vmcnt(43)
; #define U_LD(p) ({ const v2u w_ = *(const v2u*)(p); (f32x4){bflo(w_.x), bfhi(w_.x), bflo(w_.y), bfhi(w_.y)}; })
; __device__ __forceinline__ void p3_pool(Frame& F) {
;     ...
;         for (int i = 0; i < nsteps; ++i) {
;             const int s = s0 - 15 + i;
;             const int so = s - w;
;             f32x4 n0 = (f32x4){0.f, 0.f, 0.f, 0.f}, o0 = n0;
;             if (isP) {
;                 if (s >= 0) n0 = U_LD(U + (mbase + s) * 512 + c0);
;                 if (i >= w && so >= 0) o0 = U_LD(U + (mbase + so) * 512 + c0);
;             } else {
;                 if (s >= 0) n0 = U_LD(U + (mbase + s) * 512 + c0); else n0 = *(const f32x4*)(state_pool + ((size_t)b * 15 + (s + 15)) * 512 + c0);
;                 if (i >= w) { if (so >= 0) o0 = U_LD(U + (mbase + so) * 512 + c0); else o0 = *(const f32x4*)(state_pool + ((size_t)b * 15 + (so + 15)) * 512 + c0); }
;             }
;             S0 += n0 - o0;
;             if (i >= 15) {
	v_lshlrev_b32_e32 v144, 16, v46
	v_and_b32_e32 v145, 0xffff0000, v46
	v_lshlrev_b32_e32 v146, 16, v47
	v_and_b32_e32 v147, 0xffff0000, v47
	v_cndmask_b32_e64 v148, v42, v166, s[94:95]
	v_cndmask_b32_e64 v149, v43, v167, s[94:95]
	v_lshlrev_b32_e32 v150, 16, v148
	v_and_b32_e32 v151, 0xffff0000, v148
	v_lshlrev_b32_e32 v152, 16, v149
	v_and_b32_e32 v153, 0xffff0000, v149
	v_pk_add_f32 v[154:155], v[144:145], v[150:151] neg_lo:[0,1] neg_hi:[0,1]
	v_pk_add_f32 v[156:157], v[146:147], v[152:153] neg_lo:[0,1] neg_hi:[0,1]
	v_pk_add_f32 v[140:141], v[140:141], v[154:155]
	v_pk_add_f32 v[142:143], v[142:143], v[156:157]
	s_waitcnt vmcnt(42)
	v_lshlrev_b32_e32 v144, 16, v48
	v_and_b32_e32 v145, 0xffff0000, v48
	v_lshlrev_b32_e32 v146, 16, v49
	v_and_b32_e32 v147, 0xffff0000, v49
	v_cndmask_b32_e64 v148, v44, v40, s[94:95]
	v_cndmask_b32_e64 v149, v45, v41, s[94:95]
	v_lshlrev_b32_e32 v150, 16, v148
	v_and_b32_e32 v151, 0xffff0000, v148
	v_lshlrev_b32_e32 v152, 16, v149
	v_and_b32_e32 v153, 0xffff0000, v149
	v_pk_add_f32 v[154:155], v[144:145], v[150:151] neg_lo:[0,1] neg_hi:[0,1]
	v_pk_add_f32 v[156:157], v[146:147], v[152:153] neg_lo:[0,1] neg_hi:[0,1]
	v_pk_add_f32 v[140:141], v[140:141], v[154:155]
	v_pk_add_f32 v[142:143], v[142:143], v[156:157]
	s_waitcnt vmcnt(41)
	v_lshlrev_b32_e32 v144, 16, v50
	v_and_b32_e32 v145, 0xffff0000, v50
	v_lshlrev_b32_e32 v146, 16, v51
	v_and_b32_e32 v147, 0xffff0000, v51
	v_cndmask_b32_e64 v148, v46, v42, s[94:95]
	v_cndmask_b32_e64 v149, v47, v43, s[94:95]
	v_lshlrev_b32_e32 v150, 16, v148
	v_and_b32_e32 v151, 0xffff0000, v148
	v_lshlrev_b32_e32 v152, 16, v149
	v_and_b32_e32 v153, 0xffff0000, v149
	v_pk_add_f32 v[154:155], v[144:145], v[150:151] neg_lo:[0,1] neg_hi:[0,1]
	v_pk_add_f32 v[156:157], v[146:147], v[152:153] neg_lo:[0,1] neg_hi:[0,1]
	v_pk_add_f32 v[140:141], v[140:141], v[154:155]
	v_pk_add_f32 v[142:143], v[142:143], v[156:157]
	s_waitcnt vmcnt(40)
	v_lshlrev_b32_e32 v144, 16, v52
	v_and_b32_e32 v145, 0xffff0000, v52
	v_lshlrev_b32_e32 v146, 16, v53
	v_and_b32_e32 v147, 0xffff0000, v53
	v_cndmask_b32_e64 v148, v48, v44, s[94:95]
	v_cndmask_b32_e64 v149, v49, v45, s[94:95]
	v_lshlrev_b32_e32 v150, 16, v148
	v_and_b32_e32 v151, 0xffff0000, v148
	v_lshlrev_b32_e32 v152, 16, v149
	v_and_b32_e32 v153, 0xffff0000, v149
	v_pk_add_f32 v[154:155], v[144:145], v[150:151] neg_lo:[0,1] neg_hi:[0,1]
	v_pk_add_f32 v[156:157], v[146:147], v[152:153] neg_lo:[0,1] neg_hi:[0,1]
	v_pk_add_f32 v[140:141], v[140:141], v[154:155]
	v_pk_add_f32 v[142:143], v[142:143], v[156:157]
	s_waitcnt vmcnt(39)
	v_lshlrev_b32_e32 v144, 16, v54
	v_and_b32_e32 v145, 0xffff0000, v54
	v_lshlrev_b32_e32 v146, 16, v55
	v_and_b32_e32 v147, 0xffff0000, v55
	v_cndmask_b32_e64 v148, v50, v46, s[94:95]
	v_cndmask_b32_e64 v149, v51, v47, s[94:95]
	v_lshlrev_b32_e32 v150, 16, v148
	v_and_b32_e32 v151, 0xffff0000, v148
	v_lshlrev_b32_e32 v152, 16, v149
	v_and_b32_e32 v153, 0xffff0000, v149
	v_pk_add_f32 v[154:155], v[144:145], v[150:151] neg_lo:[0,1] neg_hi:[0,1]
	v_pk_add_f32 v[156:157], v[146:147], v[152:153] neg_lo:[0,1] neg_hi:[0,1]
	v_pk_add_f32 v[140:141], v[140:141], v[154:155]
	v_pk_add_f32 v[142:143], v[142:143], v[156:157]
	s_waitcnt vmcnt(38)
	v_lshlrev_b32_e32 v144, 16, v56
	v_and_b32_e32 v145, 0xffff0000, v56
	v_lshlrev_b32_e32 v146, 16, v57
	v_and_b32_e32 v147, 0xffff0000, v57
	v_cndmask_b32_e64 v148, v52, v48, s[94:95]
	v_cndmask_b32_e64 v149, v53, v49, s[94:95]
	v_lshlrev_b32_e32 v150, 16, v148
	v_and_b32_e32 v151, 0xffff0000, v148
	v_lshlrev_b32_e32 v152, 16, v149
	v_and_b32_e32 v153, 0xffff0000, v149
	v_pk_add_f32 v[154:155], v[144:145], v[150:151] neg_lo:[0,1] neg_hi:[0,1]
	v_pk_add_f32 v[156:157], v[146:147], v[152:153] neg_lo:[0,1] neg_hi:[0,1]
	v_pk_add_f32 v[140:141], v[140:141], v[154:155]
	v_pk_add_f32 v[142:143], v[142:143], v[156:157]
	s_waitcnt vmcnt(37)
	v_lshlrev_b32_e32 v144, 16, v58
	v_and_b32_e32 v145, 0xffff0000, v58
	v_lshlrev_b32_e32 v146, 16, v59
	v_and_b32_e32 v147, 0xffff0000, v59
	v_cndmask_b32_e64 v148, v54, v50, s[94:95]
	v_cndmask_b32_e64 v149, v55, v51, s[94:95]
	v_lshlrev_b32_e32 v150, 16, v148
	v_and_b32_e32 v151, 0xffff0000, v148
	v_lshlrev_b32_e32 v152, 16, v149
	v_and_b32_e32 v153, 0xffff0000, v149
	v_pk_add_f32 v[154:155], v[144:145], v[150:151] neg_lo:[0,1] neg_hi:[0,1]
	v_pk_add_f32 v[156:157], v[146:147], v[152:153] neg_lo:[0,1] neg_hi:[0,1]
	v_pk_add_f32 v[140:141], v[140:141], v[154:155]
	v_pk_add_f32 v[142:143], v[142:143], v[156:157]
	s_waitcnt vmcnt(36)
	v_lshlrev_b32_e32 v144, 16, v60
	v_and_b32_e32 v145, 0xffff0000, v60
	v_lshlrev_b32_e32 v146, 16, v61
	v_and_b32_e32 v147, 0xffff0000, v61
	v_cndmask_b32_e64 v148, v56, v52, s[94:95]
	v_cndmask_b32_e64 v149, v57, v53, s[94:95]
	v_lshlrev_b32_e32 v150, 16, v148
	v_and_b32_e32 v151, 0xffff0000, v148
	v_lshlrev_b32_e32 v152, 16, v149
	v_and_b32_e32 v153, 0xffff0000, v149
	v_pk_add_f32 v[154:155], v[144:145], v[150:151] neg_lo:[0,1] neg_hi:[0,1]
	v_pk_add_f32 v[156:157], v[146:147], v[152:153] neg_lo:[0,1] neg_hi:[0,1]
	v_pk_add_f32 v[140:141], v[140:141], v[154:155]
	v_pk_add_f32 v[142:143], v[142:143], v[156:157]
	s_waitcnt vmcnt(35)
	v_lshlrev_b32_e32 v144, 16, v62
	v_and_b32_e32 v145, 0xffff0000, v62
	v_lshlrev_b32_e32 v146, 16, v63
	v_and_b32_e32 v147, 0xffff0000, v63
	v_cndmask_b32_e64 v148, v58, v54, s[94:95]
	v_cndmask_b32_e64 v149, v59, v55, s[94:95]
	v_lshlrev_b32_e32 v150, 16, v148
	v_and_b32_e32 v151, 0xffff0000, v148
	v_lshlrev_b32_e32 v152, 16, v149
	v_and_b32_e32 v153, 0xffff0000, v149
	v_pk_add_f32 v[154:155], v[144:145], v[150:151] neg_lo:[0,1] neg_hi:[0,1]
	v_pk_add_f32 v[156:157], v[146:147], v[152:153] neg_lo:[0,1] neg_hi:[0,1]
	v_pk_add_f32 v[140:141], v[140:141], v[154:155]
	v_pk_add_f32 v[142:143], v[142:143], v[156:157]
	s_waitcnt vmcnt(34)
; #define GAS __attribute__((address_space(1)))
; __device__ __forceinline__ unsigned pk2(float lo, float hi) { f32x2_t v = {lo, hi}; bf16x2_t b = __builtin_convertvector(v, bf16x2_t); return __builtin_bit_cast(unsigned, b); }
; #define U_LD(p) ({ const v2u w_ = *(const v2u*)(p); (f32x4){bflo(w_.x), bfhi(w_.x), bflo(w_.y), bfhi(w_.y)}; })
; __device__ __forceinline__ void p3_pool(Frame& F) {
;     ...
;         for (int i = 0; i < nsteps; ++i) {
;             const int s = s0 - 15 + i;
;             const int so = s - w;
;             f32x4 n0 = (f32x4){0.f, 0.f, 0.f, 0.f}, o0 = n0;
;             if (isP) {
;                 if (s >= 0) n0 = U_LD(U + (mbase + s) * 512 + c0);
;                 if (i >= w && so >= 0) o0 = U_LD(U + (mbase + so) * 512 + c0);
;             } else {
;                 if (s >= 0) n0 = U_LD(U + (mbase + s) * 512 + c0); else n0 = *(const f32x4*)(state_pool + ((size_t)b * 15 + (s + 15)) * 512 + c0);
;                 if (i >= w) { if (so >= 0) o0 = U_LD(U + (mbase + so) * 512 + c0); else o0 = *(const f32x4*)(state_pool + ((size_t)b * 15 + (so + 15)) * 512 + c0); }
;             }
;             S0 += n0 - o0;
;             if (i >= 15) {
;                 const int cnt = isP ? (w < s + 1 ? w : s + 1) : w; const float inv = 1.f / (float)cnt;
;                 const f32x4 d0 = S0 * inv - n0;
;                 v2u wv; wv.x = pk2(d0[0], d0[1]); wv.y = pk2(d0[2], d0[3]);
;                 *(GAS v2u*)(D + (size_t)(c0 >> 8) * ((size_t)MT * 256) + (mbase + s) * 256 + (c0 & 255)) = wv;
;             }
	v_lshlrev_b32_e32 v144, 16, v64
	v_and_b32_e32 v145, 0xffff0000, v64
	v_lshlrev_b32_e32 v146, 16, v65
	v_and_b32_e32 v147, 0xffff0000, v65
	v_cndmask_b32_e64 v148, v60, v56, s[94:95]
	v_cndmask_b32_e64 v149, v61, v57, s[94:95]
	v_lshlrev_b32_e32 v150, 16, v148
	v_and_b32_e32 v151, 0xffff0000, v148
	v_lshlrev_b32_e32 v152, 16, v149
	v_and_b32_e32 v153, 0xffff0000, v149
	v_pk_add_f32 v[154:155], v[144:145], v[150:151] neg_lo:[0,1] neg_hi:[0,1]
	v_pk_add_f32 v[156:157], v[146:147], v[152:153] neg_lo:[0,1] neg_hi:[0,1]
	v_pk_add_f32 v[140:141], v[140:141], v[154:155]
	v_pk_add_f32 v[142:143], v[142:143], v[156:157]
	s_waitcnt vmcnt(33)
	v_lshlrev_b32_e32 v144, 16, v66
	v_and_b32_e32 v145, 0xffff0000, v66
	v_lshlrev_b32_e32 v146, 16, v67
	v_and_b32_e32 v147, 0xffff0000, v67
	v_cndmask_b32_e64 v148, v62, v58, s[94:95]
	v_cndmask_b32_e64 v149, v63, v59, s[94:95]
	v_lshlrev_b32_e32 v150, 16, v148
	v_and_b32_e32 v151, 0xffff0000, v148
	v_lshlrev_b32_e32 v152, 16, v149
	v_and_b32_e32 v153, 0xffff0000, v149
	v_pk_add_f32 v[154:155], v[144:145], v[150:151] neg_lo:[0,1] neg_hi:[0,1]
	v_pk_add_f32 v[156:157], v[146:147], v[152:153] neg_lo:[0,1] neg_hi:[0,1]
	v_pk_add_f32 v[140:141], v[140:141], v[154:155]
	v_pk_add_f32 v[142:143], v[142:143], v[156:157]
	s_waitcnt vmcnt(32)
	v_lshlrev_b32_e32 v144, 16, v68
	v_and_b32_e32 v145, 0xffff0000, v68
	v_lshlrev_b32_e32 v146, 16, v69
	v_and_b32_e32 v147, 0xffff0000, v69
	v_cndmask_b32_e64 v148, v64, v60, s[94:95]
	v_cndmask_b32_e64 v149, v65, v61, s[94:95]
	v_lshlrev_b32_e32 v150, 16, v148
	v_and_b32_e32 v151, 0xffff0000, v148
	v_lshlrev_b32_e32 v152, 16, v149
	v_and_b32_e32 v153, 0xffff0000, v149
	v_pk_add_f32 v[154:155], v[144:145], v[150:151] neg_lo:[0,1] neg_hi:[0,1]
	v_pk_add_f32 v[156:157], v[146:147], v[152:153] neg_lo:[0,1] neg_hi:[0,1]
	v_pk_add_f32 v[140:141], v[140:141], v[154:155]
	v_pk_add_f32 v[142:143], v[142:143], v[156:157]
	s_waitcnt vmcnt(31)
	v_lshlrev_b32_e32 v144, 16, v70
	v_and_b32_e32 v145, 0xffff0000, v70
	v_lshlrev_b32_e32 v146, 16, v71
	v_and_b32_e32 v147, 0xffff0000, v71
	v_cndmask_b32_e64 v148, v66, v62, s[94:95]
	v_cndmask_b32_e64 v149, v67, v63, s[94:95]
	v_lshlrev_b32_e32 v150, 16, v148
	v_and_b32_e32 v151, 0xffff0000, v148
	v_lshlrev_b32_e32 v152, 16, v149
	v_and_b32_e32 v153, 0xffff0000, v149
	v_pk_add_f32 v[154:155], v[144:145], v[150:151] neg_lo:[0,1] neg_hi:[0,1]
	v_pk_add_f32 v[156:157], v[146:147], v[152:153] neg_lo:[0,1] neg_hi:[0,1]
	v_pk_add_f32 v[140:141], v[140:141], v[154:155]
	v_pk_add_f32 v[142:143], v[142:143], v[156:157]
	v_pk_fma_f32 v[158:159], v[164:165], v[140:141], v[144:145] op_sel_hi:[0,1,1] neg_lo:[0,0,1] neg_hi:[0,0,1]
	v_pk_fma_f32 v[160:161], v[164:165], v[142:143], v[146:147] op_sel_hi:[0,1,1] neg_lo:[0,0,1] neg_hi:[0,0,1]
	v_cvt_pk_bf16_f32 v162, v158, v159
	v_cvt_pk_bf16_f32 v163, v160, v161
	global_store_dwordx2 v36, v[162:163], s[96:97]
	s_waitcnt vmcnt(31)
	v_lshlrev_b32_e32 v144, 16, v72
	v_and_b32_e32 v145, 0xffff0000, v72
	v_lshlrev_b32_e32 v146, 16, v73
	v_and_b32_e32 v147, 0xffff0000, v73
	v_cndmask_b32_e64 v148, v68, v64, s[94:95]
	v_cndmask_b32_e64 v149, v69, v65, s[94:95]
	v_lshlrev_b32_e32 v150, 16, v148
	v_and_b32_e32 v151, 0xffff0000, v148
	v_lshlrev_b32_e32 v152, 16, v149
	v_and_b32_e32 v153, 0xffff0000, v149
	v_pk_add_f32 v[154:155], v[144:145], v[150:151] neg_lo:[0,1] neg_hi:[0,1]
	v_pk_add_f32 v[156:157], v[146:147], v[152:153] neg_lo:[0,1] neg_hi:[0,1]
	v_pk_add_f32 v[140:141], v[140:141], v[154:155]
	v_pk_add_f32 v[142:143], v[142:143], v[156:157]
	v_pk_fma_f32 v[158:159], v[164:165], v[140:141], v[144:145] op_sel_hi:[0,1,1] neg_lo:[0,0,1] neg_hi:[0,0,1]
	v_pk_fma_f32 v[160:161], v[164:165], v[142:143], v[146:147] op_sel_hi:[0,1,1] neg_lo:[0,0,1] neg_hi:[0,0,1]
	v_cvt_pk_bf16_f32 v162, v158, v159
	v_cvt_pk_bf16_f32 v163, v160, v161
	global_store_dwordx2 v36, v[162:163], s[96:97] offset:512
	s_waitcnt vmcnt(31)
	v_lshlrev_b32_e32 v144, 16, v74
	v_and_b32_e32 v145, 0xffff0000, v74
	v_lshlrev_b32_e32 v146, 16, v75
	v_and_b32_e32 v147, 0xffff0000, v75
	v_cndmask_b32_e64 v148, v70, v66, s[94:95]
	v_cndmask_b32_e64 v149, v71, v67, s[94:95]
	v_lshlrev_b32_e32 v150, 16, v148
	v_and_b32_e32 v151, 0xffff0000, v148
	v_lshlrev_b32_e32 v152, 16, v149
	v_and_b32_e32 v153, 0xffff0000, v149
	v_pk_add_f32 v[154:155], v[144:145], v[150:151] neg_lo:[0,1] neg_hi:[0,1]
	v_pk_add_f32 v[156:157], v[146:147], v[152:153] neg_lo:[0,1] neg_hi:[0,1]
	v_pk_add_f32 v[140:141], v[140:141], v[154:155]
	v_pk_add_f32 v[142:143], v[142:143], v[156:157]
	v_pk_fma_f32 v[158:159], v[164:165], v[140:141], v[144:145] op_sel_hi:[0,1,1] neg_lo:[0,0,1] neg_hi:[0,0,1]
	v_pk_fma_f32 v[160:161], v[164:165], v[142:143], v[146:147] op_sel_hi:[0,1,1] neg_lo:[0,0,1] neg_hi:[0,0,1]
	v_cvt_pk_bf16_f32 v162, v158, v159
	v_cvt_pk_bf16_f32 v163, v160, v161
	global_store_dwordx2 v36, v[162:163], s[96:97] offset:1024
	s_waitcnt vmcnt(31)
	v_lshlrev_b32_e32 v144, 16, v76
	v_and_b32_e32 v145, 0xffff0000, v76
	v_lshlrev_b32_e32 v146, 16, v77
	v_and_b32_e32 v147, 0xffff0000, v77
	v_cndmask_b32_e64 v148, v72, v68, s[94:95]
	v_cndmask_b32_e64 v149, v73, v69, s[94:95]
	v_lshlrev_b32_e32 v150, 16, v148
	v_and_b32_e32 v151, 0xffff0000, v148
	v_lshlrev_b32_e32 v152, 16, v149
	v_and_b32_e32 v153, 0xffff0000, v149
	v_pk_add_f32 v[154:155], v[144:145], v[150:151] neg_lo:[0,1] neg_hi:[0,1]
	v_pk_add_f32 v[156:157], v[146:147], v[152:153] neg_lo:[0,1] neg_hi:[0,1]
	v_pk_add_f32 v[140:141], v[140:141], v[154:155]
	v_pk_add_f32 v[142:143], v[142:143], v[156:157]
	v_pk_fma_f32 v[158:159], v[164:165], v[140:141], v[144:145] op_sel_hi:[0,1,1] neg_lo:[0,0,1] neg_hi:[0,0,1]
	v_pk_fma_f32 v[160:161], v[164:165], v[142:143], v[146:147] op_sel_hi:[0,1,1] neg_lo:[0,0,1] neg_hi:[0,0,1]
	v_cvt_pk_bf16_f32 v162, v158, v159
	v_cvt_pk_bf16_f32 v163, v160, v161
	global_store_dwordx2 v36, v[162:163], s[96:97] offset:1536
	s_waitcnt vmcnt(31)
; #define GAS __attribute__((address_space(1)))
; __device__ __forceinline__ unsigned pk2(float lo, float hi) { f32x2_t v = {lo, hi}; bf16x2_t b = __builtin_convertvector(v, bf16x2_t); return __builtin_bit_cast(unsigned, b); }
; #define U_LD(p) ({ const v2u w_ = *(const v2u*)(p); (f32x4){bflo(w_.x), bfhi(w_.x), bflo(w_.y), bfhi(w_.y)}; })
; __device__ __forceinline__ void p3_pool(Frame& F) {
;     ...
;         for (int i = 0; i < nsteps; ++i) {
;             const int s = s0 - 15 + i;
;             const int so = s - w;
;             f32x4 n0 = (f32x4){0.f, 0.f, 0.f, 0.f}, o0 = n0;
;             if (isP) {
;                 if (s >= 0) n0 = U_LD(U + (mbase + s) * 512 + c0);
;                 if (i >= w && so >= 0) o0 = U_LD(U + (mbase + so) * 512 + c0);
;             } else {
;                 if (s >= 0) n0 = U_LD(U + (mbase + s) * 512 + c0); else n0 = *(const f32x4*)(state_pool + ((size_t)b * 15 + (s + 15)) * 512 + c0);
;                 if (i >= w) { if (so >= 0) o0 = U_LD(U + (mbase + so) * 512 + c0); else o0 = *(const f32x4*)(state_pool + ((size_t)b * 15 + (so + 15)) * 512 + c0); }
;             }
;             S0 += n0 - o0;
;             if (i >= 15) {
;                 const int cnt = isP ? (w < s + 1 ? w : s + 1) : w; const float inv = 1.f / (float)cnt;
;                 const f32x4 d0 = S0 * inv - n0;
;                 v2u wv; wv.x = pk2(d0[0], d0[1]); wv.y = pk2(d0[2], d0[3]);
;                 *(GAS v2u*)(D + (size_t)(c0 >> 8) * ((size_t)MT * 256) + (mbase + s) * 256 + (c0 & 255)) = wv;
;             }
	v_lshlrev_b32_e32 v144, 16, v78
	v_and_b32_e32 v145, 0xffff0000, v78
	v_lshlrev_b32_e32 v146, 16, v79
	v_and_b32_e32 v147, 0xffff0000, v79
	v_cndmask_b32_e64 v148, v74, v70, s[94:95]
	v_cndmask_b32_e64 v149, v75, v71, s[94:95]
	v_lshlrev_b32_e32 v150, 16, v148
	v_and_b32_e32 v151, 0xffff0000, v148
	v_lshlrev_b32_e32 v152, 16, v149
	v_and_b32_e32 v153, 0xffff0000, v149
	v_pk_add_f32 v[154:155], v[144:145], v[150:151] neg_lo:[0,1] neg_hi:[0,1]
	v_pk_add_f32 v[156:157], v[146:147], v[152:153] neg_lo:[0,1] neg_hi:[0,1]
	v_pk_add_f32 v[140:141], v[140:141], v[154:155]
	v_pk_add_f32 v[142:143], v[142:143], v[156:157]
	v_pk_fma_f32 v[158:159], v[164:165], v[140:141], v[144:145] op_sel_hi:[0,1,1] neg_lo:[0,0,1] neg_hi:[0,0,1]
	v_pk_fma_f32 v[160:161], v[164:165], v[142:143], v[146:147] op_sel_hi:[0,1,1] neg_lo:[0,0,1] neg_hi:[0,0,1]
	v_cvt_pk_bf16_f32 v162, v158, v159
	v_cvt_pk_bf16_f32 v163, v160, v161
	global_store_dwordx2 v36, v[162:163], s[96:97] offset:2048
	s_waitcnt vmcnt(31)
	v_lshlrev_b32_e32 v144, 16, v80
	v_and_b32_e32 v145, 0xffff0000, v80
	v_lshlrev_b32_e32 v146, 16, v81
	v_and_b32_e32 v147, 0xffff0000, v81
	v_cndmask_b32_e64 v148, v76, v72, s[94:95]
	v_cndmask_b32_e64 v149, v77, v73, s[94:95]
	v_lshlrev_b32_e32 v150, 16, v148
	v_and_b32_e32 v151, 0xffff0000, v148
	v_lshlrev_b32_e32 v152, 16, v149
	v_and_b32_e32 v153, 0xffff0000, v149
	v_pk_add_f32 v[154:155], v[144:145], v[150:151] neg_lo:[0,1] neg_hi:[0,1]
	v_pk_add_f32 v[156:157], v[146:147], v[152:153] neg_lo:[0,1] neg_hi:[0,1]
	v_pk_add_f32 v[140:141], v[140:141], v[154:155]
	v_pk_add_f32 v[142:143], v[142:143], v[156:157]
	v_pk_fma_f32 v[158:159], v[164:165], v[140:141], v[144:145] op_sel_hi:[0,1,1] neg_lo:[0,0,1] neg_hi:[0,0,1]
	v_pk_fma_f32 v[160:161], v[164:165], v[142:143], v[146:147] op_sel_hi:[0,1,1] neg_lo:[0,0,1] neg_hi:[0,0,1]
	v_cvt_pk_bf16_f32 v162, v158, v159
	v_cvt_pk_bf16_f32 v163, v160, v161
	global_store_dwordx2 v36, v[162:163], s[96:97] offset:2560
	s_waitcnt vmcnt(31)
	v_lshlrev_b32_e32 v144, 16, v82
	v_and_b32_e32 v145, 0xffff0000, v82
	v_lshlrev_b32_e32 v146, 16, v83
	v_and_b32_e32 v147, 0xffff0000, v83
	v_cndmask_b32_e64 v148, v78, v74, s[94:95]
	v_cndmask_b32_e64 v149, v79, v75, s[94:95]
	v_lshlrev_b32_e32 v150, 16, v148
	v_and_b32_e32 v151, 0xffff0000, v148
	v_lshlrev_b32_e32 v152, 16, v149
	v_and_b32_e32 v153, 0xffff0000, v149
	v_pk_add_f32 v[154:155], v[144:145], v[150:151] neg_lo:[0,1] neg_hi:[0,1]
	v_pk_add_f32 v[156:157], v[146:147], v[152:153] neg_lo:[0,1] neg_hi:[0,1]
	v_pk_add_f32 v[140:141], v[140:141], v[154:155]
	v_pk_add_f32 v[142:143], v[142:143], v[156:157]
	v_pk_fma_f32 v[158:159], v[164:165], v[140:141], v[144:145] op_sel_hi:[0,1,1] neg_lo:[0,0,1] neg_hi:[0,0,1]
	v_pk_fma_f32 v[160:161], v[164:165], v[142:143], v[146:147] op_sel_hi:[0,1,1] neg_lo:[0,0,1] neg_hi:[0,0,1]
	v_cvt_pk_bf16_f32 v162, v158, v159
	v_cvt_pk_bf16_f32 v163, v160, v161
	global_store_dwordx2 v36, v[162:163], s[96:97] offset:3072
	s_waitcnt vmcnt(31)
	v_lshlrev_b32_e32 v144, 16, v84
	v_and_b32_e32 v145, 0xffff0000, v84
	v_lshlrev_b32_e32 v146, 16, v85
	v_and_b32_e32 v147, 0xffff0000, v85
	v_cndmask_b32_e64 v148, v80, v76, s[94:95]
	v_cndmask_b32_e64 v149, v81, v77, s[94:95]
	v_lshlrev_b32_e32 v150, 16, v148
	v_and_b32_e32 v151, 0xffff0000, v148
	v_lshlrev_b32_e32 v152, 16, v149
	v_and_b32_e32 v153, 0xffff0000, v149
	v_pk_add_f32 v[154:155], v[144:145], v[150:151] neg_lo:[0,1] neg_hi:[0,1]
	v_pk_add_f32 v[156:157], v[146:147], v[152:153] neg_lo:[0,1] neg_hi:[0,1]
	v_pk_add_f32 v[140:141], v[140:141], v[154:155]
	v_pk_add_f32 v[142:143], v[142:143], v[156:157]
	v_pk_fma_f32 v[158:159], v[164:165], v[140:141], v[144:145] op_sel_hi:[0,1,1] neg_lo:[0,0,1] neg_hi:[0,0,1]
	v_pk_fma_f32 v[160:161], v[164:165], v[142:143], v[146:147] op_sel_hi:[0,1,1] neg_lo:[0,0,1] neg_hi:[0,0,1]
	v_cvt_pk_bf16_f32 v162, v158, v159
	v_cvt_pk_bf16_f32 v163, v160, v161
	global_store_dwordx2 v36, v[162:163], s[96:97] offset:3584
	s_add_u32 s96, s96, 0x1000
	s_addc_u32 s97, s97, 0
	s_waitcnt vmcnt(31)
	v_lshlrev_b32_e32 v144, 16, v86
	v_and_b32_e32 v145, 0xffff0000, v86
	v_lshlrev_b32_e32 v146, 16, v87
	v_and_b32_e32 v147, 0xffff0000, v87
	v_cndmask_b32_e64 v148, v82, v78, s[94:95]
	v_cndmask_b32_e64 v149, v83, v79, s[94:95]
	v_lshlrev_b32_e32 v150, 16, v148
	v_and_b32_e32 v151, 0xffff0000, v148
	v_lshlrev_b32_e32 v152, 16, v149
	v_and_b32_e32 v153, 0xffff0000, v149
	v_pk_add_f32 v[154:155], v[144:145], v[150:151] neg_lo:[0,1] neg_hi:[0,1]
	v_pk_add_f32 v[156:157], v[146:147], v[152:153] neg_lo:[0,1] neg_hi:[0,1]
	v_pk_add_f32 v[140:141], v[140:141], v[154:155]
	v_pk_add_f32 v[142:143], v[142:143], v[156:157]
	v_pk_fma_f32 v[158:159], v[164:165], v[140:141], v[144:145] op_sel_hi:[0,1,1] neg_lo:[0,0,1] neg_hi:[0,0,1]
	v_pk_fma_f32 v[160:161], v[164:165], v[142:143], v[146:147] op_sel_hi:[0,1,1] neg_lo:[0,0,1] neg_hi:[0,0,1]
	v_cvt_pk_bf16_f32 v162, v158, v159
	v_cvt_pk_bf16_f32 v163, v160, v161
	global_store_dwordx2 v36, v[162:163], s[96:97]
	s_waitcnt vmcnt(31)
	v_lshlrev_b32_e32 v144, 16, v88
	v_and_b32_e32 v145, 0xffff0000, v88
	v_lshlrev_b32_e32 v146, 16, v89
	v_and_b32_e32 v147, 0xffff0000, v89
	v_cndmask_b32_e64 v148, v84, v80, s[94:95]
	v_cndmask_b32_e64 v149, v85, v81, s[94:95]
	v_lshlrev_b32_e32 v150, 16, v148
	v_and_b32_e32 v151, 0xffff0000, v148
	v_lshlrev_b32_e32 v152, 16, v149
	v_and_b32_e32 v153, 0xffff0000, v149
	v_pk_add_f32 v[154:155], v[144:145], v[150:151] neg_lo:[0,1] neg_hi:[0,1]
	v_pk_add_f32 v[156:157], v[146:147], v[152:153] neg_lo:[0,1] neg_hi:[0,1]
	v_pk_add_f32 v[140:141], v[140:141], v[154:155]
	v_pk_add_f32 v[142:143], v[142:143], v[156:157]
	v_pk_fma_f32 v[158:159], v[164:165], v[140:141], v[144:145] op_sel_hi:[0,1,1] neg_lo:[0,0,1] neg_hi:[0,0,1]
	v_pk_fma_f32 v[160:161], v[164:165], v[142:143], v[146:147] op_sel_hi:[0,1,1] neg_lo:[0,0,1] neg_hi:[0,0,1]
	v_cvt_pk_bf16_f32 v162, v158, v159
	v_cvt_pk_bf16_f32 v163, v160, v161
	global_store_dwordx2 v36, v[162:163], s[96:97] offset:512
	s_waitcnt vmcnt(31)
; #define GAS __attribute__((address_space(1)))
; __device__ __forceinline__ unsigned pk2(float lo, float hi) { f32x2_t v = {lo, hi}; bf16x2_t b = __builtin_convertvector(v, bf16x2_t); return __builtin_bit_cast(unsigned, b); }
; #define U_LD(p) ({ const v2u w_ = *(const v2u*)(p); (f32x4){bflo(w_.x), bfhi(w_.x), bflo(w_.y), bfhi(w_.y)}; })
; __device__ __forceinline__ void p3_pool(Frame& F) {
;     ...
;         for (int i = 0; i < nsteps; ++i) {
;             const int s = s0 - 15 + i;
;             const int so = s - w;
;             f32x4 n0 = (f32x4){0.f, 0.f, 0.f, 0.f}, o0 = n0;
;             if (isP) {
;                 if (s >= 0) n0 = U_LD(U + (mbase + s) * 512 + c0);
;                 if (i >= w && so >= 0) o0 = U_LD(U + (mbase + so) * 512 + c0);
;             } else {
;                 if (s >= 0) n0 = U_LD(U + (mbase + s) * 512 + c0); else n0 = *(const f32x4*)(state_pool + ((size_t)b * 15 + (s + 15)) * 512 + c0);
;                 if (i >= w) { if (so >= 0) o0 = U_LD(U + (mbase + so) * 512 + c0); else o0 = *(const f32x4*)(state_pool + ((size_t)b * 15 + (so + 15)) * 512 + c0); }
;             }
;             S0 += n0 - o0;
;             if (i >= 15) {
;                 const int cnt = isP ? (w < s + 1 ? w : s + 1) : w; const float inv = 1.f / (float)cnt;
;                 const f32x4 d0 = S0 * inv - n0;
;                 v2u wv; wv.x = pk2(d0[0], d0[1]); wv.y = pk2(d0[2], d0[3]);
;                 *(GAS v2u*)(D + (size_t)(c0 >> 8) * ((size_t)MT * 256) + (mbase + s) * 256 + (c0 & 255)) = wv;
;             }
	v_lshlrev_b32_e32 v144, 16, v90
	v_and_b32_e32 v145, 0xffff0000, v90
	v_lshlrev_b32_e32 v146, 16, v91
	v_and_b32_e32 v147, 0xffff0000, v91
	v_cndmask_b32_e64 v148, v86, v82, s[94:95]
	v_cndmask_b32_e64 v149, v87, v83, s[94:95]
	v_lshlrev_b32_e32 v150, 16, v148
	v_and_b32_e32 v151, 0xffff0000, v148
	v_lshlrev_b32_e32 v152, 16, v149
	v_and_b32_e32 v153, 0xffff0000, v149
	v_pk_add_f32 v[154:155], v[144:145], v[150:151] neg_lo:[0,1] neg_hi:[0,1]
	v_pk_add_f32 v[156:157], v[146:147], v[152:153] neg_lo:[0,1] neg_hi:[0,1]
	v_pk_add_f32 v[140:141], v[140:141], v[154:155]
	v_pk_add_f32 v[142:143], v[142:143], v[156:157]
	v_pk_fma_f32 v[158:159], v[164:165], v[140:141], v[144:145] op_sel_hi:[0,1,1] neg_lo:[0,0,1] neg_hi:[0,0,1]
	v_pk_fma_f32 v[160:161], v[164:165], v[142:143], v[146:147] op_sel_hi:[0,1,1] neg_lo:[0,0,1] neg_hi:[0,0,1]
	v_cvt_pk_bf16_f32 v162, v158, v159
	v_cvt_pk_bf16_f32 v163, v160, v161
	global_store_dwordx2 v36, v[162:163], s[96:97] offset:1024
	s_waitcnt vmcnt(31)
	v_lshlrev_b32_e32 v144, 16, v92
	v_and_b32_e32 v145, 0xffff0000, v92
	v_lshlrev_b32_e32 v146, 16, v93
	v_and_b32_e32 v147, 0xffff0000, v93
	v_cndmask_b32_e64 v148, v88, v84, s[94:95]
	v_cndmask_b32_e64 v149, v89, v85, s[94:95]
	v_lshlrev_b32_e32 v150, 16, v148
	v_and_b32_e32 v151, 0xffff0000, v148
	v_lshlrev_b32_e32 v152, 16, v149
	v_and_b32_e32 v153, 0xffff0000, v149
	v_pk_add_f32 v[154:155], v[144:145], v[150:151] neg_lo:[0,1] neg_hi:[0,1]
	v_pk_add_f32 v[156:157], v[146:147], v[152:153] neg_lo:[0,1] neg_hi:[0,1]
	v_pk_add_f32 v[140:141], v[140:141], v[154:155]
	v_pk_add_f32 v[142:143], v[142:143], v[156:157]
	v_pk_fma_f32 v[158:159], v[164:165], v[140:141], v[144:145] op_sel_hi:[0,1,1] neg_lo:[0,0,1] neg_hi:[0,0,1]
	v_pk_fma_f32 v[160:161], v[164:165], v[142:143], v[146:147] op_sel_hi:[0,1,1] neg_lo:[0,0,1] neg_hi:[0,0,1]
	v_cvt_pk_bf16_f32 v162, v158, v159
	v_cvt_pk_bf16_f32 v163, v160, v161
	global_store_dwordx2 v36, v[162:163], s[96:97] offset:1536
	s_waitcnt vmcnt(31)
	v_lshlrev_b32_e32 v144, 16, v94
	v_and_b32_e32 v145, 0xffff0000, v94
	v_lshlrev_b32_e32 v146, 16, v95
	v_and_b32_e32 v147, 0xffff0000, v95
	v_cndmask_b32_e64 v148, v90, v86, s[94:95]
	v_cndmask_b32_e64 v149, v91, v87, s[94:95]
	v_lshlrev_b32_e32 v150, 16, v148
	v_and_b32_e32 v151, 0xffff0000, v148
	v_lshlrev_b32_e32 v152, 16, v149
	v_and_b32_e32 v153, 0xffff0000, v149
	v_pk_add_f32 v[154:155], v[144:145], v[150:151] neg_lo:[0,1] neg_hi:[0,1]
	v_pk_add_f32 v[156:157], v[146:147], v[152:153] neg_lo:[0,1] neg_hi:[0,1]
	v_pk_add_f32 v[140:141], v[140:141], v[154:155]
	v_pk_add_f32 v[142:143], v[142:143], v[156:157]
	v_pk_fma_f32 v[158:159], v[164:165], v[140:141], v[144:145] op_sel_hi:[0,1,1] neg_lo:[0,0,1] neg_hi:[0,0,1]
	v_pk_fma_f32 v[160:161], v[164:165], v[142:143], v[146:147] op_sel_hi:[0,1,1] neg_lo:[0,0,1] neg_hi:[0,0,1]
	v_cvt_pk_bf16_f32 v162, v158, v159
	v_cvt_pk_bf16_f32 v163, v160, v161
	global_store_dwordx2 v36, v[162:163], s[96:97] offset:2048
	s_waitcnt vmcnt(31)
	v_lshlrev_b32_e32 v144, 16, v96
	v_and_b32_e32 v145, 0xffff0000, v96
	v_lshlrev_b32_e32 v146, 16, v97
	v_and_b32_e32 v147, 0xffff0000, v97
	v_cndmask_b32_e64 v148, v92, v88, s[94:95]
	v_cndmask_b32_e64 v149, v93, v89, s[94:95]
	v_lshlrev_b32_e32 v150, 16, v148
	v_and_b32_e32 v151, 0xffff0000, v148
	v_lshlrev_b32_e32 v152, 16, v149
	v_and_b32_e32 v153, 0xffff0000, v149
	v_pk_add_f32 v[154:155], v[144:145], v[150:151] neg_lo:[0,1] neg_hi:[0,1]
	v_pk_add_f32 v[156:157], v[146:147], v[152:153] neg_lo:[0,1] neg_hi:[0,1]
	v_pk_add_f32 v[140:141], v[140:141], v[154:155]
	v_pk_add_f32 v[142:143], v[142:143], v[156:157]
	v_pk_fma_f32 v[158:159], v[164:165], v[140:141], v[144:145] op_sel_hi:[0,1,1] neg_lo:[0,0,1] neg_hi:[0,0,1]
	v_pk_fma_f32 v[160:161], v[164:165], v[142:143], v[146:147] op_sel_hi:[0,1,1] neg_lo:[0,0,1] neg_hi:[0,0,1]
	v_cvt_pk_bf16_f32 v162, v158, v159
	v_cvt_pk_bf16_f32 v163, v160, v161
	global_store_dwordx2 v36, v[162:163], s[96:97] offset:2560
	s_waitcnt vmcnt(31)
	v_lshlrev_b32_e32 v144, 16, v98
	v_and_b32_e32 v145, 0xffff0000, v98
	v_lshlrev_b32_e32 v146, 16, v99
	v_and_b32_e32 v147, 0xffff0000, v99
	v_cndmask_b32_e64 v148, v94, v90, s[94:95]
	v_cndmask_b32_e64 v149, v95, v91, s[94:95]
	v_lshlrev_b32_e32 v150, 16, v148
	v_and_b32_e32 v151, 0xffff0000, v148
	v_lshlrev_b32_e32 v152, 16, v149
	v_and_b32_e32 v153, 0xffff0000, v149
	v_pk_add_f32 v[154:155], v[144:145], v[150:151] neg_lo:[0,1] neg_hi:[0,1]
	v_pk_add_f32 v[156:157], v[146:147], v[152:153] neg_lo:[0,1] neg_hi:[0,1]
	v_pk_add_f32 v[140:141], v[140:141], v[154:155]
	v_pk_add_f32 v[142:143], v[142:143], v[156:157]
	v_pk_fma_f32 v[158:159], v[164:165], v[140:141], v[144:145] op_sel_hi:[0,1,1] neg_lo:[0,0,1] neg_hi:[0,0,1]
	v_pk_fma_f32 v[160:161], v[164:165], v[142:143], v[146:147] op_sel_hi:[0,1,1] neg_lo:[0,0,1] neg_hi:[0,0,1]
	v_cvt_pk_bf16_f32 v162, v158, v159
	v_cvt_pk_bf16_f32 v163, v160, v161
	global_store_dwordx2 v36, v[162:163], s[96:97] offset:3072
	s_waitcnt vmcnt(31)
	v_lshlrev_b32_e32 v144, 16, v100
	v_and_b32_e32 v145, 0xffff0000, v100
	v_lshlrev_b32_e32 v146, 16, v101
	v_and_b32_e32 v147, 0xffff0000, v101
	v_cndmask_b32_e64 v148, v96, v92, s[94:95]
	v_cndmask_b32_e64 v149, v97, v93, s[94:95]
	v_lshlrev_b32_e32 v150, 16, v148
	v_and_b32_e32 v151, 0xffff0000, v148
	v_lshlrev_b32_e32 v152, 16, v149
	v_and_b32_e32 v153, 0xffff0000, v149
	v_pk_add_f32 v[154:155], v[144:145], v[150:151] neg_lo:[0,1] neg_hi:[0,1]
	v_pk_add_f32 v[156:157], v[146:147], v[152:153] neg_lo:[0,1] neg_hi:[0,1]
	v_pk_add_f32 v[140:141], v[140:141], v[154:155]
	v_pk_add_f32 v[142:143], v[142:143], v[156:157]
	v_pk_fma_f32 v[158:159], v[164:165], v[140:141], v[144:145] op_sel_hi:[0,1,1] neg_lo:[0,0,1] neg_hi:[0,0,1]
	v_pk_fma_f32 v[160:161], v[164:165], v[142:143], v[146:147] op_sel_hi:[0,1,1] neg_lo:[0,0,1] neg_hi:[0,0,1]
	v_cvt_pk_bf16_f32 v162, v158, v159
	v_cvt_pk_bf16_f32 v163, v160, v161
	global_store_dwordx2 v36, v[162:163], s[96:97] offset:3584
	s_add_u32 s96, s96, 0x1000
	s_addc_u32 s97, s97, 0
	s_waitcnt vmcnt(31)
; #define GAS __attribute__((address_space(1)))
; __device__ __forceinline__ unsigned pk2(float lo, float hi) { f32x2_t v = {lo, hi}; bf16x2_t b = __builtin_convertvector(v, bf16x2_t); return __builtin_bit_cast(unsigned, b); }
; #define U_LD(p) ({ const v2u w_ = *(const v2u*)(p); (f32x4){bflo(w_.x), bfhi(w_.x), bflo(w_.y), bfhi(w_.y)}; })
; __device__ __forceinline__ void p3_pool(Frame& F) {
;     ...
;         for (int i = 0; i < nsteps; ++i) {
;             const int s = s0 - 15 + i;
;             const int so = s - w;
;             f32x4 n0 = (f32x4){0.f, 0.f, 0.f, 0.f}, o0 = n0;
;             if (isP) {
;                 if (s >= 0) n0 = U_LD(U + (mbase + s) * 512 + c0);
;                 if (i >= w && so >= 0) o0 = U_LD(U + (mbase + so) * 512 + c0);
;             } else {
;                 if (s >= 0) n0 = U_LD(U + (mbase + s) * 512 + c0); else n0 = *(const f32x4*)(state_pool + ((size_t)b * 15 + (s + 15)) * 512 + c0);
;                 if (i >= w) { if (so >= 0) o0 = U_LD(U + (mbase + so) * 512 + c0); else o0 = *(const f32x4*)(state_pool + ((size_t)b * 15 + (so + 15)) * 512 + c0); }
;             }
;             S0 += n0 - o0;
;             if (i >= 15) {
;                 const int cnt = isP ? (w < s + 1 ? w : s + 1) : w; const float inv = 1.f / (float)cnt;
;                 const f32x4 d0 = S0 * inv - n0;
;                 v2u wv; wv.x = pk2(d0[0], d0[1]); wv.y = pk2(d0[2], d0[3]);
;                 *(GAS v2u*)(D + (size_t)(c0 >> 8) * ((size_t)MT * 256) + (mbase + s) * 256 + (c0 & 255)) = wv;
;             }
	v_lshlrev_b32_e32 v144, 16, v102
	v_and_b32_e32 v145, 0xffff0000, v102
	v_lshlrev_b32_e32 v146, 16, v103
	v_and_b32_e32 v147, 0xffff0000, v103
	v_cndmask_b32_e64 v148, v98, v94, s[94:95]
	v_cndmask_b32_e64 v149, v99, v95, s[94:95]
	v_lshlrev_b32_e32 v150, 16, v148
	v_and_b32_e32 v151, 0xffff0000, v148
	v_lshlrev_b32_e32 v152, 16, v149
	v_and_b32_e32 v153, 0xffff0000, v149
	v_pk_add_f32 v[154:155], v[144:145], v[150:151] neg_lo:[0,1] neg_hi:[0,1]
	v_pk_add_f32 v[156:157], v[146:147], v[152:153] neg_lo:[0,1] neg_hi:[0,1]
	v_pk_add_f32 v[140:141], v[140:141], v[154:155]
	v_pk_add_f32 v[142:143], v[142:143], v[156:157]
	v_pk_fma_f32 v[158:159], v[164:165], v[140:141], v[144:145] op_sel_hi:[0,1,1] neg_lo:[0,0,1] neg_hi:[0,0,1]
	v_pk_fma_f32 v[160:161], v[164:165], v[142:143], v[146:147] op_sel_hi:[0,1,1] neg_lo:[0,0,1] neg_hi:[0,0,1]
	v_cvt_pk_bf16_f32 v162, v158, v159
	v_cvt_pk_bf16_f32 v163, v160, v161
	global_store_dwordx2 v36, v[162:163], s[96:97]
	s_waitcnt vmcnt(31)
	v_lshlrev_b32_e32 v144, 16, v104
	v_and_b32_e32 v145, 0xffff0000, v104
	v_lshlrev_b32_e32 v146, 16, v105
	v_and_b32_e32 v147, 0xffff0000, v105
	v_cndmask_b32_e64 v148, v100, v96, s[94:95]
	v_cndmask_b32_e64 v149, v101, v97, s[94:95]
	v_lshlrev_b32_e32 v150, 16, v148
	v_and_b32_e32 v151, 0xffff0000, v148
	v_lshlrev_b32_e32 v152, 16, v149
	v_and_b32_e32 v153, 0xffff0000, v149
	v_pk_add_f32 v[154:155], v[144:145], v[150:151] neg_lo:[0,1] neg_hi:[0,1]
	v_pk_add_f32 v[156:157], v[146:147], v[152:153] neg_lo:[0,1] neg_hi:[0,1]
	v_pk_add_f32 v[140:141], v[140:141], v[154:155]
	v_pk_add_f32 v[142:143], v[142:143], v[156:157]
	v_pk_fma_f32 v[158:159], v[164:165], v[140:141], v[144:145] op_sel_hi:[0,1,1] neg_lo:[0,0,1] neg_hi:[0,0,1]
	v_pk_fma_f32 v[160:161], v[164:165], v[142:143], v[146:147] op_sel_hi:[0,1,1] neg_lo:[0,0,1] neg_hi:[0,0,1]
	v_cvt_pk_bf16_f32 v162, v158, v159
	v_cvt_pk_bf16_f32 v163, v160, v161
	global_store_dwordx2 v36, v[162:163], s[96:97] offset:512
	s_waitcnt vmcnt(31)
	v_lshlrev_b32_e32 v144, 16, v106
	v_and_b32_e32 v145, 0xffff0000, v106
	v_lshlrev_b32_e32 v146, 16, v107
	v_and_b32_e32 v147, 0xffff0000, v107
	v_cndmask_b32_e64 v148, v102, v98, s[94:95]
	v_cndmask_b32_e64 v149, v103, v99, s[94:95]
	v_lshlrev_b32_e32 v150, 16, v148
	v_and_b32_e32 v151, 0xffff0000, v148
	v_lshlrev_b32_e32 v152, 16, v149
	v_and_b32_e32 v153, 0xffff0000, v149
	v_pk_add_f32 v[154:155], v[144:145], v[150:151] neg_lo:[0,1] neg_hi:[0,1]
	v_pk_add_f32 v[156:157], v[146:147], v[152:153] neg_lo:[0,1] neg_hi:[0,1]
	v_pk_add_f32 v[140:141], v[140:141], v[154:155]
	v_pk_add_f32 v[142:143], v[142:143], v[156:157]
	v_pk_fma_f32 v[158:159], v[164:165], v[140:141], v[144:145] op_sel_hi:[0,1,1] neg_lo:[0,0,1] neg_hi:[0,0,1]
	v_pk_fma_f32 v[160:161], v[164:165], v[142:143], v[146:147] op_sel_hi:[0,1,1] neg_lo:[0,0,1] neg_hi:[0,0,1]
	v_cvt_pk_bf16_f32 v162, v158, v159
	v_cvt_pk_bf16_f32 v163, v160, v161
	global_store_dwordx2 v36, v[162:163], s[96:97] offset:1024
	s_waitcnt vmcnt(31)
	v_lshlrev_b32_e32 v144, 16, v108
	v_and_b32_e32 v145, 0xffff0000, v108
	v_lshlrev_b32_e32 v146, 16, v109
	v_and_b32_e32 v147, 0xffff0000, v109
	v_cndmask_b32_e64 v148, v104, v100, s[94:95]
	v_cndmask_b32_e64 v149, v105, v101, s[94:95]
	v_lshlrev_b32_e32 v150, 16, v148
	v_and_b32_e32 v151, 0xffff0000, v148
	v_lshlrev_b32_e32 v152, 16, v149
	v_and_b32_e32 v153, 0xffff0000, v149
	v_pk_add_f32 v[154:155], v[144:145], v[150:151] neg_lo:[0,1] neg_hi:[0,1]
	v_pk_add_f32 v[156:157], v[146:147], v[152:153] neg_lo:[0,1] neg_hi:[0,1]
	v_pk_add_f32 v[140:141], v[140:141], v[154:155]
	v_pk_add_f32 v[142:143], v[142:143], v[156:157]
	v_pk_fma_f32 v[158:159], v[164:165], v[140:141], v[144:145] op_sel_hi:[0,1,1] neg_lo:[0,0,1] neg_hi:[0,0,1]
	v_pk_fma_f32 v[160:161], v[164:165], v[142:143], v[146:147] op_sel_hi:[0,1,1] neg_lo:[0,0,1] neg_hi:[0,0,1]
	v_cvt_pk_bf16_f32 v162, v158, v159
	v_cvt_pk_bf16_f32 v163, v160, v161
	global_store_dwordx2 v36, v[162:163], s[96:97] offset:1536
	s_waitcnt vmcnt(31)
	v_lshlrev_b32_e32 v144, 16, v110
	v_and_b32_e32 v145, 0xffff0000, v110
	v_lshlrev_b32_e32 v146, 16, v111
	v_and_b32_e32 v147, 0xffff0000, v111
	v_cndmask_b32_e64 v148, v106, v102, s[94:95]
	v_cndmask_b32_e64 v149, v107, v103, s[94:95]
	v_lshlrev_b32_e32 v150, 16, v148
	v_and_b32_e32 v151, 0xffff0000, v148
	v_lshlrev_b32_e32 v152, 16, v149
	v_and_b32_e32 v153, 0xffff0000, v149
	v_pk_add_f32 v[154:155], v[144:145], v[150:151] neg_lo:[0,1] neg_hi:[0,1]
	v_pk_add_f32 v[156:157], v[146:147], v[152:153] neg_lo:[0,1] neg_hi:[0,1]
	v_pk_add_f32 v[140:141], v[140:141], v[154:155]
	v_pk_add_f32 v[142:143], v[142:143], v[156:157]
	v_pk_fma_f32 v[158:159], v[164:165], v[140:141], v[144:145] op_sel_hi:[0,1,1] neg_lo:[0,0,1] neg_hi:[0,0,1]
	v_pk_fma_f32 v[160:161], v[164:165], v[142:143], v[146:147] op_sel_hi:[0,1,1] neg_lo:[0,0,1] neg_hi:[0,0,1]
	v_cvt_pk_bf16_f32 v162, v158, v159
	v_cvt_pk_bf16_f32 v163, v160, v161
	global_store_dwordx2 v36, v[162:163], s[96:97] offset:2048
	s_waitcnt vmcnt(31)
	v_lshlrev_b32_e32 v144, 16, v112
	v_and_b32_e32 v145, 0xffff0000, v112
	v_lshlrev_b32_e32 v146, 16, v113
	v_and_b32_e32 v147, 0xffff0000, v113
	v_cndmask_b32_e64 v148, v108, v104, s[94:95]
	v_cndmask_b32_e64 v149, v109, v105, s[94:95]
	v_lshlrev_b32_e32 v150, 16, v148
	v_and_b32_e32 v151, 0xffff0000, v148
	v_lshlrev_b32_e32 v152, 16, v149
	v_and_b32_e32 v153, 0xffff0000, v149
	v_pk_add_f32 v[154:155], v[144:145], v[150:151] neg_lo:[0,1] neg_hi:[0,1]
	v_pk_add_f32 v[156:157], v[146:147], v[152:153] neg_lo:[0,1] neg_hi:[0,1]
	v_pk_add_f32 v[140:141], v[140:141], v[154:155]
	v_pk_add_f32 v[142:143], v[142:143], v[156:157]
	v_pk_fma_f32 v[158:159], v[164:165], v[140:141], v[144:145] op_sel_hi:[0,1,1] neg_lo:[0,0,1] neg_hi:[0,0,1]
	v_pk_fma_f32 v[160:161], v[164:165], v[142:143], v[146:147] op_sel_hi:[0,1,1] neg_lo:[0,0,1] neg_hi:[0,0,1]
	v_cvt_pk_bf16_f32 v162, v158, v159
	v_cvt_pk_bf16_f32 v163, v160, v161
	global_store_dwordx2 v36, v[162:163], s[96:97] offset:2560
	s_waitcnt vmcnt(31)
; #define GAS __attribute__((address_space(1)))
; __device__ __forceinline__ unsigned pk2(float lo, float hi) { f32x2_t v = {lo, hi}; bf16x2_t b = __builtin_convertvector(v, bf16x2_t); return __builtin_bit_cast(unsigned, b); }
; #define U_LD(p) ({ const v2u w_ = *(const v2u*)(p); (f32x4){bflo(w_.x), bfhi(w_.x), bflo(w_.y), bfhi(w_.y)}; })
; __device__ __forceinline__ void p3_pool(Frame& F) {
;     ...
;         for (int i = 0; i < nsteps; ++i) {
;             const int s = s0 - 15 + i;
;             const int so = s - w;
;             f32x4 n0 = (f32x4){0.f, 0.f, 0.f, 0.f}, o0 = n0;
;             if (isP) {
;                 if (s >= 0) n0 = U_LD(U + (mbase + s) * 512 + c0);
;                 if (i >= w && so >= 0) o0 = U_LD(U + (mbase + so) * 512 + c0);
;             } else {
;                 if (s >= 0) n0 = U_LD(U + (mbase + s) * 512 + c0); else n0 = *(const f32x4*)(state_pool + ((size_t)b * 15 + (s + 15)) * 512 + c0);
;                 if (i >= w) { if (so >= 0) o0 = U_LD(U + (mbase + so) * 512 + c0); else o0 = *(const f32x4*)(state_pool + ((size_t)b * 15 + (so + 15)) * 512 + c0); }
;             }
;             S0 += n0 - o0;
;             if (i >= 15) {
;                 const int cnt = isP ? (w < s + 1 ? w : s + 1) : w; const float inv = 1.f / (float)cnt;
;                 const f32x4 d0 = S0 * inv - n0;
;                 v2u wv; wv.x = pk2(d0[0], d0[1]); wv.y = pk2(d0[2], d0[3]);
;                 *(GAS v2u*)(D + (size_t)(c0 >> 8) * ((size_t)MT * 256) + (mbase + s) * 256 + (c0 & 255)) = wv;
;             }
	v_lshlrev_b32_e32 v144, 16, v114
	v_and_b32_e32 v145, 0xffff0000, v114
	v_lshlrev_b32_e32 v146, 16, v115
	v_and_b32_e32 v147, 0xffff0000, v115
	v_cndmask_b32_e64 v148, v110, v106, s[94:95]
	v_cndmask_b32_e64 v149, v111, v107, s[94:95]
	v_lshlrev_b32_e32 v150, 16, v148
	v_and_b32_e32 v151, 0xffff0000, v148
	v_lshlrev_b32_e32 v152, 16, v149
	v_and_b32_e32 v153, 0xffff0000, v149
	v_pk_add_f32 v[154:155], v[144:145], v[150:151] neg_lo:[0,1] neg_hi:[0,1]
	v_pk_add_f32 v[156:157], v[146:147], v[152:153] neg_lo:[0,1] neg_hi:[0,1]
	v_pk_add_f32 v[140:141], v[140:141], v[154:155]
	v_pk_add_f32 v[142:143], v[142:143], v[156:157]
	v_pk_fma_f32 v[158:159], v[164:165], v[140:141], v[144:145] op_sel_hi:[0,1,1] neg_lo:[0,0,1] neg_hi:[0,0,1]
	v_pk_fma_f32 v[160:161], v[164:165], v[142:143], v[146:147] op_sel_hi:[0,1,1] neg_lo:[0,0,1] neg_hi:[0,0,1]
	v_cvt_pk_bf16_f32 v162, v158, v159
	v_cvt_pk_bf16_f32 v163, v160, v161
	global_store_dwordx2 v36, v[162:163], s[96:97] offset:3072
	s_waitcnt vmcnt(31)
	v_lshlrev_b32_e32 v144, 16, v116
	v_and_b32_e32 v145, 0xffff0000, v116
	v_lshlrev_b32_e32 v146, 16, v117
	v_and_b32_e32 v147, 0xffff0000, v117
	v_cndmask_b32_e64 v148, v112, v108, s[94:95]
	v_cndmask_b32_e64 v149, v113, v109, s[94:95]
	v_lshlrev_b32_e32 v150, 16, v148
	v_and_b32_e32 v151, 0xffff0000, v148
	v_lshlrev_b32_e32 v152, 16, v149
	v_and_b32_e32 v153, 0xffff0000, v149
	v_pk_add_f32 v[154:155], v[144:145], v[150:151] neg_lo:[0,1] neg_hi:[0,1]
	v_pk_add_f32 v[156:157], v[146:147], v[152:153] neg_lo:[0,1] neg_hi:[0,1]
	v_pk_add_f32 v[140:141], v[140:141], v[154:155]
	v_pk_add_f32 v[142:143], v[142:143], v[156:157]
	v_pk_fma_f32 v[158:159], v[164:165], v[140:141], v[144:145] op_sel_hi:[0,1,1] neg_lo:[0,0,1] neg_hi:[0,0,1]
	v_pk_fma_f32 v[160:161], v[164:165], v[142:143], v[146:147] op_sel_hi:[0,1,1] neg_lo:[0,0,1] neg_hi:[0,0,1]
	v_cvt_pk_bf16_f32 v162, v158, v159
	v_cvt_pk_bf16_f32 v163, v160, v161
	global_store_dwordx2 v36, v[162:163], s[96:97] offset:3584
	s_add_u32 s96, s96, 0x1000
	s_addc_u32 s97, s97, 0
	s_waitcnt vmcnt(31)
	v_lshlrev_b32_e32 v144, 16, v118
	v_and_b32_e32 v145, 0xffff0000, v118
	v_lshlrev_b32_e32 v146, 16, v119
	v_and_b32_e32 v147, 0xffff0000, v119
	v_cndmask_b32_e64 v148, v114, v110, s[94:95]
	v_cndmask_b32_e64 v149, v115, v111, s[94:95]
	v_lshlrev_b32_e32 v150, 16, v148
	v_and_b32_e32 v151, 0xffff0000, v148
	v_lshlrev_b32_e32 v152, 16, v149
	v_and_b32_e32 v153, 0xffff0000, v149
	v_pk_add_f32 v[154:155], v[144:145], v[150:151] neg_lo:[0,1] neg_hi:[0,1]
	v_pk_add_f32 v[156:157], v[146:147], v[152:153] neg_lo:[0,1] neg_hi:[0,1]
	v_pk_add_f32 v[140:141], v[140:141], v[154:155]
	v_pk_add_f32 v[142:143], v[142:143], v[156:157]
	v_pk_fma_f32 v[158:159], v[164:165], v[140:141], v[144:145] op_sel_hi:[0,1,1] neg_lo:[0,0,1] neg_hi:[0,0,1]
	v_pk_fma_f32 v[160:161], v[164:165], v[142:143], v[146:147] op_sel_hi:[0,1,1] neg_lo:[0,0,1] neg_hi:[0,0,1]
	v_cvt_pk_bf16_f32 v162, v158, v159
	v_cvt_pk_bf16_f32 v163, v160, v161
	global_store_dwordx2 v36, v[162:163], s[96:97]
	s_waitcnt vmcnt(31)
	v_lshlrev_b32_e32 v144, 16, v120
	v_and_b32_e32 v145, 0xffff0000, v120
	v_lshlrev_b32_e32 v146, 16, v121
	v_and_b32_e32 v147, 0xffff0000, v121
	v_cndmask_b32_e64 v148, v116, v112, s[94:95]
	v_cndmask_b32_e64 v149, v117, v113, s[94:95]
	v_lshlrev_b32_e32 v150, 16, v148
	v_and_b32_e32 v151, 0xffff0000, v148
	v_lshlrev_b32_e32 v152, 16, v149
	v_and_b32_e32 v153, 0xffff0000, v149
	v_pk_add_f32 v[154:155], v[144:145], v[150:151] neg_lo:[0,1] neg_hi:[0,1]
	v_pk_add_f32 v[156:157], v[146:147], v[152:153] neg_lo:[0,1] neg_hi:[0,1]
	v_pk_add_f32 v[140:141], v[140:141], v[154:155]
	v_pk_add_f32 v[142:143], v[142:143], v[156:157]
	v_pk_fma_f32 v[158:159], v[164:165], v[140:141], v[144:145] op_sel_hi:[0,1,1] neg_lo:[0,0,1] neg_hi:[0,0,1]
	v_pk_fma_f32 v[160:161], v[164:165], v[142:143], v[146:147] op_sel_hi:[0,1,1] neg_lo:[0,0,1] neg_hi:[0,0,1]
	v_cvt_pk_bf16_f32 v162, v158, v159
	v_cvt_pk_bf16_f32 v163, v160, v161
	global_store_dwordx2 v36, v[162:163], s[96:97] offset:512
	s_waitcnt vmcnt(31)
	v_lshlrev_b32_e32 v144, 16, v122
	v_and_b32_e32 v145, 0xffff0000, v122
	v_lshlrev_b32_e32 v146, 16, v123
	v_and_b32_e32 v147, 0xffff0000, v123
	v_cndmask_b32_e64 v148, v118, v114, s[94:95]
	v_cndmask_b32_e64 v149, v119, v115, s[94:95]
	v_lshlrev_b32_e32 v150, 16, v148
	v_and_b32_e32 v151, 0xffff0000, v148
	v_lshlrev_b32_e32 v152, 16, v149
	v_and_b32_e32 v153, 0xffff0000, v149
	v_pk_add_f32 v[154:155], v[144:145], v[150:151] neg_lo:[0,1] neg_hi:[0,1]
	v_pk_add_f32 v[156:157], v[146:147], v[152:153] neg_lo:[0,1] neg_hi:[0,1]
	v_pk_add_f32 v[140:141], v[140:141], v[154:155]
	v_pk_add_f32 v[142:143], v[142:143], v[156:157]
	v_pk_fma_f32 v[158:159], v[164:165], v[140:141], v[144:145] op_sel_hi:[0,1,1] neg_lo:[0,0,1] neg_hi:[0,0,1]
	v_pk_fma_f32 v[160:161], v[164:165], v[142:143], v[146:147] op_sel_hi:[0,1,1] neg_lo:[0,0,1] neg_hi:[0,0,1]
	v_cvt_pk_bf16_f32 v162, v158, v159
	v_cvt_pk_bf16_f32 v163, v160, v161
	global_store_dwordx2 v36, v[162:163], s[96:97] offset:1024
	s_waitcnt vmcnt(31)
; #define GAS __attribute__((address_space(1)))
; __device__ __forceinline__ unsigned pk2(float lo, float hi) { f32x2_t v = {lo, hi}; bf16x2_t b = __builtin_convertvector(v, bf16x2_t); return __builtin_bit_cast(unsigned, b); }
; #define U_LD(p) ({ const v2u w_ = *(const v2u*)(p); (f32x4){bflo(w_.x), bfhi(w_.x), bflo(w_.y), bfhi(w_.y)}; })
; __device__ __forceinline__ void p3_pool(Frame& F) {
;     ...
;         for (int i = 0; i < nsteps; ++i) {
;             const int s = s0 - 15 + i;
;             const int so = s - w;
;             f32x4 n0 = (f32x4){0.f, 0.f, 0.f, 0.f}, o0 = n0;
;             if (isP) {
;                 if (s >= 0) n0 = U_LD(U + (mbase + s) * 512 + c0);
;                 if (i >= w && so >= 0) o0 = U_LD(U + (mbase + so) * 512 + c0);
;             } else {
;                 if (s >= 0) n0 = U_LD(U + (mbase + s) * 512 + c0); else n0 = *(const f32x4*)(state_pool + ((size_t)b * 15 + (s + 15)) * 512 + c0);
;                 if (i >= w) { if (so >= 0) o0 = U_LD(U + (mbase + so) * 512 + c0); else o0 = *(const f32x4*)(state_pool + ((size_t)b * 15 + (so + 15)) * 512 + c0); }
;             }
;             S0 += n0 - o0;
;             if (i >= 15) {
;                 const int cnt = isP ? (w < s + 1 ? w : s + 1) : w; const float inv = 1.f / (float)cnt;
;                 const f32x4 d0 = S0 * inv - n0;
;                 v2u wv; wv.x = pk2(d0[0], d0[1]); wv.y = pk2(d0[2], d0[3]);
;                 *(GAS v2u*)(D + (size_t)(c0 >> 8) * ((size_t)MT * 256) + (mbase + s) * 256 + (c0 & 255)) = wv;
;             }
;             if (!isP && s >= -7 && s < 0) *(GAS f32x4*)(out + O_POOLS + ((size_t)b * 15 + (s + 7)) * 512 + c0) = n0;
;         }
;     }
	v_lshlrev_b32_e32 v144, 16, v124
	v_and_b32_e32 v145, 0xffff0000, v124
	v_lshlrev_b32_e32 v146, 16, v125
	v_and_b32_e32 v147, 0xffff0000, v125
	v_cndmask_b32_e64 v148, v120, v116, s[94:95]
	v_cndmask_b32_e64 v149, v121, v117, s[94:95]
	v_lshlrev_b32_e32 v150, 16, v148
	v_and_b32_e32 v151, 0xffff0000, v148
	v_lshlrev_b32_e32 v152, 16, v149
	v_and_b32_e32 v153, 0xffff0000, v149
	v_pk_add_f32 v[154:155], v[144:145], v[150:151] neg_lo:[0,1] neg_hi:[0,1]
	v_pk_add_f32 v[156:157], v[146:147], v[152:153] neg_lo:[0,1] neg_hi:[0,1]
	v_pk_add_f32 v[140:141], v[140:141], v[154:155]
	v_pk_add_f32 v[142:143], v[142:143], v[156:157]
	v_pk_fma_f32 v[158:159], v[164:165], v[140:141], v[144:145] op_sel_hi:[0,1,1] neg_lo:[0,0,1] neg_hi:[0,0,1]
	v_pk_fma_f32 v[160:161], v[164:165], v[142:143], v[146:147] op_sel_hi:[0,1,1] neg_lo:[0,0,1] neg_hi:[0,0,1]
	v_cvt_pk_bf16_f32 v162, v158, v159
	v_cvt_pk_bf16_f32 v163, v160, v161
	global_store_dwordx2 v36, v[162:163], s[96:97] offset:1536
	s_waitcnt vmcnt(31)
	v_lshlrev_b32_e32 v144, 16, v126
	v_and_b32_e32 v145, 0xffff0000, v126
	v_lshlrev_b32_e32 v146, 16, v127
	v_and_b32_e32 v147, 0xffff0000, v127
	v_cndmask_b32_e64 v148, v122, v118, s[94:95]
	v_cndmask_b32_e64 v149, v123, v119, s[94:95]
	v_lshlrev_b32_e32 v150, 16, v148
	v_and_b32_e32 v151, 0xffff0000, v148
	v_lshlrev_b32_e32 v152, 16, v149
	v_and_b32_e32 v153, 0xffff0000, v149
	v_pk_add_f32 v[154:155], v[144:145], v[150:151] neg_lo:[0,1] neg_hi:[0,1]
	v_pk_add_f32 v[156:157], v[146:147], v[152:153] neg_lo:[0,1] neg_hi:[0,1]
	v_pk_add_f32 v[140:141], v[140:141], v[154:155]
	v_pk_add_f32 v[142:143], v[142:143], v[156:157]
	v_pk_fma_f32 v[158:159], v[164:165], v[140:141], v[144:145] op_sel_hi:[0,1,1] neg_lo:[0,0,1] neg_hi:[0,0,1]
	v_pk_fma_f32 v[160:161], v[164:165], v[142:143], v[146:147] op_sel_hi:[0,1,1] neg_lo:[0,0,1] neg_hi:[0,0,1]
	v_cvt_pk_bf16_f32 v162, v158, v159
	v_cvt_pk_bf16_f32 v163, v160, v161
	global_store_dwordx2 v36, v[162:163], s[96:97] offset:2048
	s_waitcnt vmcnt(31)
	v_lshlrev_b32_e32 v144, 16, v128
	v_and_b32_e32 v145, 0xffff0000, v128
	v_lshlrev_b32_e32 v146, 16, v129
	v_and_b32_e32 v147, 0xffff0000, v129
	v_cndmask_b32_e64 v148, v124, v120, s[94:95]
	v_cndmask_b32_e64 v149, v125, v121, s[94:95]
	v_lshlrev_b32_e32 v150, 16, v148
	v_and_b32_e32 v151, 0xffff0000, v148
	v_lshlrev_b32_e32 v152, 16, v149
	v_and_b32_e32 v153, 0xffff0000, v149
	v_pk_add_f32 v[154:155], v[144:145], v[150:151] neg_lo:[0,1] neg_hi:[0,1]
	v_pk_add_f32 v[156:157], v[146:147], v[152:153] neg_lo:[0,1] neg_hi:[0,1]
	v_pk_add_f32 v[140:141], v[140:141], v[154:155]
	v_pk_add_f32 v[142:143], v[142:143], v[156:157]
	v_pk_fma_f32 v[158:159], v[164:165], v[140:141], v[144:145] op_sel_hi:[0,1,1] neg_lo:[0,0,1] neg_hi:[0,0,1]
	v_pk_fma_f32 v[160:161], v[164:165], v[142:143], v[146:147] op_sel_hi:[0,1,1] neg_lo:[0,0,1] neg_hi:[0,0,1]
	v_cvt_pk_bf16_f32 v162, v158, v159
	v_cvt_pk_bf16_f32 v163, v160, v161
	global_store_dwordx2 v36, v[162:163], s[96:97] offset:2560
	s_waitcnt vmcnt(31)
	v_lshlrev_b32_e32 v144, 16, v130
	v_and_b32_e32 v145, 0xffff0000, v130
	v_lshlrev_b32_e32 v146, 16, v131
	v_and_b32_e32 v147, 0xffff0000, v131
	v_cndmask_b32_e64 v148, v126, v122, s[94:95]
	v_cndmask_b32_e64 v149, v127, v123, s[94:95]
	v_lshlrev_b32_e32 v150, 16, v148
	v_and_b32_e32 v151, 0xffff0000, v148
	v_lshlrev_b32_e32 v152, 16, v149
	v_and_b32_e32 v153, 0xffff0000, v149
	v_pk_add_f32 v[154:155], v[144:145], v[150:151] neg_lo:[0,1] neg_hi:[0,1]
	v_pk_add_f32 v[156:157], v[146:147], v[152:153] neg_lo:[0,1] neg_hi:[0,1]
	v_pk_add_f32 v[140:141], v[140:141], v[154:155]
	v_pk_add_f32 v[142:143], v[142:143], v[156:157]
	v_pk_fma_f32 v[158:159], v[164:165], v[140:141], v[144:145] op_sel_hi:[0,1,1] neg_lo:[0,0,1] neg_hi:[0,0,1]
	v_pk_fma_f32 v[160:161], v[164:165], v[142:143], v[146:147] op_sel_hi:[0,1,1] neg_lo:[0,0,1] neg_hi:[0,0,1]
	v_cvt_pk_bf16_f32 v162, v158, v159
	v_cvt_pk_bf16_f32 v163, v160, v161
	global_store_dwordx2 v36, v[162:163], s[96:97] offset:3072
	s_waitcnt vmcnt(31)
	v_lshlrev_b32_e32 v144, 16, v132
	v_and_b32_e32 v145, 0xffff0000, v132
	v_lshlrev_b32_e32 v146, 16, v133
	v_and_b32_e32 v147, 0xffff0000, v133
	v_cndmask_b32_e64 v148, v128, v124, s[94:95]
	v_cndmask_b32_e64 v149, v129, v125, s[94:95]
	v_lshlrev_b32_e32 v150, 16, v148
	v_and_b32_e32 v151, 0xffff0000, v148
	v_lshlrev_b32_e32 v152, 16, v149
	v_and_b32_e32 v153, 0xffff0000, v149
	v_pk_add_f32 v[154:155], v[144:145], v[150:151] neg_lo:[0,1] neg_hi:[0,1]
	v_pk_add_f32 v[156:157], v[146:147], v[152:153] neg_lo:[0,1] neg_hi:[0,1]
	v_pk_add_f32 v[140:141], v[140:141], v[154:155]
	v_pk_add_f32 v[142:143], v[142:143], v[156:157]
	v_pk_fma_f32 v[158:159], v[164:165], v[140:141], v[144:145] op_sel_hi:[0,1,1] neg_lo:[0,0,1] neg_hi:[0,0,1]
	v_pk_fma_f32 v[160:161], v[164:165], v[142:143], v[146:147] op_sel_hi:[0,1,1] neg_lo:[0,0,1] neg_hi:[0,0,1]
	v_cvt_pk_bf16_f32 v162, v158, v159
	v_cvt_pk_bf16_f32 v163, v160, v161
	global_store_dwordx2 v36, v[162:163], s[96:97] offset:3584
	s_branch .LBB0_515

; #define GAS __attribute__((address_space(1)))
; __device__ __forceinline__ unsigned pk2(float lo, float hi) { f32x2_t v = {lo, hi}; bf16x2_t b = __builtin_convertvector(v, bf16x2_t); return __builtin_bit_cast(unsigned, b); }
; #define U_LD(p) ({ const v2u w_ = *(const v2u*)(p); (f32x4){bflo(w_.x), bfhi(w_.x), bflo(w_.y), bfhi(w_.y)}; })
; __device__ __forceinline__ void p3_pool(Frame& F) {
;     ...
;         const int tk = tk2 >> 1, c0 = (tk2 & 1) * 256 + lane * 4, w = 2 << (c0 >> 7);
;         const bool isP = tk < NPR / 32;
;         const int b = isP ? (tk >> 6) : (tk - NPR / 32), s0 = isP ? ((tk & 63) << 5) : 0, nsteps = isP ? 47 : 23;
;         const size_t mbase = isP ? (size_t)b * SEQ : (size_t)NPR + (size_t)b * 8;
;         f32x4 S0 = (f32x4){0.f, 0.f, 0.f, 0.f};
; #pragma unroll 8
;         for (int i = 0; i < nsteps; ++i) {
;             const int s = s0 - 15 + i;
;             const int so = s - w;
;             f32x4 n0 = (f32x4){0.f, 0.f, 0.f, 0.f}, o0 = n0;
;             if (isP) {
;                 if (s >= 0) n0 = U_LD(U + (mbase + s) * 512 + c0);
;                 if (i >= w && so >= 0) o0 = U_LD(U + (mbase + so) * 512 + c0);
;             } else {
;                 if (s >= 0) n0 = U_LD(U + (mbase + s) * 512 + c0); else n0 = *(const f32x4*)(state_pool + ((size_t)b * 15 + (s + 15)) * 512 + c0);
;                 if (i >= w) { if (so >= 0) o0 = U_LD(U + (mbase + so) * 512 + c0); else o0 = *(const f32x4*)(state_pool + ((size_t)b * 15 + (so + 15)) * 512 + c0); }
;             }
;             S0 += n0 - o0;
;             if (i >= 15) {
;                 const int cnt = isP ? (w < s + 1 ? w : s + 1) : w; const float inv = 1.f / (float)cnt;
;                 const f32x4 d0 = S0 * inv - n0;
;                 v2u wv; wv.x = pk2(d0[0], d0[1]); wv.y = pk2(d0[2], d0[3]);
;                 *(GAS v2u*)(D + (size_t)(c0 >> 8) * ((size_t)MT * 256) + (mbase + s) * 256 + (c0 & 255)) = wv;
;             }
;             if (!isP && s >= -7 && s < 0) *(GAS f32x4*)(out + O_POOLS + ((size_t)b * 15 + (s + 7)) * 512 + c0) = n0;
.Lp3s_entry:
	s_waitcnt lgkmcnt(0)
	s_and_b32 s82, s24, 1
	s_add_i32 s83, s25, 0xfffffc00
	v_lshlrev_b32_e32 v36, 1, v32
	v_lshlrev_b32_e32 v37, 2, v32
	s_movk_i32 s87, 0x80
	v_cmp_le_u32_e64 s[94:95], s87, v32
	s_mul_i32 s84, s83, 0x7800
	s_lshl_b32 s85, s82, 10
	s_add_u32 s84, s84, s85
	s_add_u32 s88, s14, s84
	s_addc_u32 s89, s15, 0
	s_add_u32 s92, s16, s84
	s_addc_u32 s93, s17, 0
	s_lshl_b32 s85, s83, 3
	s_add_i32 s85, s85, 0x8000
	s_lshl_b32 s86, s82, 9
	s_lshl_b32 s84, s85, 10
	s_add_u32 s84, s84, s86
	s_add_u32 s90, s12, s84
	s_addc_u32 s91, s13, 0
	s_mul_i32 s86, s82, 0x1080000
	s_lshl_b32 s87, s85, 9
	s_add_u32 s86, s86, s87
	s_add_u32 s86, s86, 0xb400000
	s_add_u32 s84, s12, s86
	s_addc_u32 s85, s13, 0
	s_mov_b64 s[96:97], s[88:89]
	global_load_dwordx4 v[40:43], v37, s[96:97] nt
	global_load_dwordx4 v[44:47], v37, s[96:97] offset:2048 nt
	s_add_u32 s96, s96, 0x1000
	s_addc_u32 s97, s97, 0
	global_load_dwordx4 v[48:51], v37, s[96:97] nt
	global_load_dwordx4 v[52:55], v37, s[96:97] offset:2048 nt
	s_add_u32 s96, s96, 0x1000
	s_addc_u32 s97, s97, 0
	global_load_dwordx4 v[56:59], v37, s[96:97] nt
	global_load_dwordx4 v[60:63], v37, s[96:97] offset:2048 nt
	s_add_u32 s96, s96, 0x1000
	s_addc_u32 s97, s97, 0
	global_load_dwordx4 v[64:67], v37, s[96:97] nt
	global_load_dwordx4 v[68:71], v37, s[96:97] offset:2048 nt
	s_add_u32 s96, s96, 0x1000
	s_addc_u32 s97, s97, 0
	global_load_dwordx4 v[72:75], v37, s[96:97] nt
	global_load_dwordx4 v[76:79], v37, s[96:97] offset:2048 nt
	s_add_u32 s96, s96, 0x1000
	s_addc_u32 s97, s97, 0
	global_load_dwordx4 v[80:83], v37, s[96:97] nt
	global_load_dwordx4 v[84:87], v37, s[96:97] offset:2048 nt
	s_add_u32 s96, s96, 0x1000
	s_addc_u32 s97, s97, 0
	global_load_dwordx4 v[88:91], v37, s[96:97] nt
	global_load_dwordx4 v[92:95], v37, s[96:97] offset:2048 nt
	s_add_u32 s96, s96, 0x1000
	s_addc_u32 s97, s97, 0
	global_load_dwordx4 v[96:99], v37, s[96:97] nt
	s_mov_b64 s[96:97], s[90:91]
	global_load_dwordx2 v[100:101], v36, s[96:97] nt
	global_load_dwordx2 v[102:103], v36, s[96:97] offset:1024 nt
	global_load_dwordx2 v[104:105], v36, s[96:97] offset:2048 nt
	global_load_dwordx2 v[106:107], v36, s[96:97] offset:3072 nt
	s_add_u32 s96, s96, 0x1000
	s_addc_u32 s97, s97, 0
	global_load_dwordx2 v[108:109], v36, s[96:97] nt
	global_load_dwordx2 v[110:111], v36, s[96:97] offset:1024 nt
	global_load_dwordx2 v[112:113], v36, s[96:97] offset:2048 nt
	global_load_dwordx2 v[114:115], v36, s[96:97] offset:3072 nt
	s_cmp_eq_u32 s82, 0
	s_cbranch_scc0 .Lp3s_h1
	v_mov_b32_e32 v140, 0
	v_mov_b32_e32 v141, 0
	v_mov_b32_e32 v142, 0
	v_mov_b32_e32 v143, 0
	v_mov_b32_e32 v166, 0
	v_mov_b32_e32 v167, 0
	v_mov_b32_e32 v168, 0
	v_mov_b32_e32 v169, 0
	v_mov_b32_e32 v144, 0x3f000000
	v_mov_b32_e32 v145, 0x3e800000
	v_cndmask_b32_e64 v164, v144, v145, s[94:95]
	s_waitcnt vmcnt(22)
	v_pk_add_f32 v[140:141], v[140:141], v[40:41]
	v_pk_add_f32 v[142:143], v[142:143], v[42:43]
	s_waitcnt vmcnt(21)
	v_pk_add_f32 v[140:141], v[140:141], v[44:45]
	v_pk_add_f32 v[142:143], v[142:143], v[46:47]
	s_waitcnt vmcnt(20)
	v_cndmask_b32_e64 v150, v40, v166, s[94:95]
	v_cndmask_b32_e64 v151, v41, v167, s[94:95]
	v_cndmask_b32_e64 v152, v42, v168, s[94:95]
	v_cndmask_b32_e64 v153, v43, v169, s[94:95]
	v_pk_add_f32 v[154:155], v[48:49], v[150:151] neg_lo:[0,1] neg_hi:[0,1]
	v_pk_add_f32 v[156:157], v[50:51], v[152:153] neg_lo:[0,1] neg_hi:[0,1]
	v_pk_add_f32 v[140:141], v[140:141], v[154:155]
	v_pk_add_f32 v[142:143], v[142:143], v[156:157]
	s_waitcnt vmcnt(19)
	v_cndmask_b32_e64 v150, v44, v166, s[94:95]
	v_cndmask_b32_e64 v151, v45, v167, s[94:95]
	v_cndmask_b32_e64 v152, v46, v168, s[94:95]
	v_cndmask_b32_e64 v153, v47, v169, s[94:95]
	v_pk_add_f32 v[154:155], v[52:53], v[150:151] neg_lo:[0,1] neg_hi:[0,1]
	v_pk_add_f32 v[156:157], v[54:55], v[152:153] neg_lo:[0,1] neg_hi:[0,1]
	v_pk_add_f32 v[140:141], v[140:141], v[154:155]
	v_pk_add_f32 v[142:143], v[142:143], v[156:157]
	s_waitcnt vmcnt(18)
	v_cndmask_b32_e64 v150, v48, v40, s[94:95]
	v_cndmask_b32_e64 v151, v49, v41, s[94:95]
	v_cndmask_b32_e64 v152, v50, v42, s[94:95]
	v_cndmask_b32_e64 v153, v51, v43, s[94:95]
	v_pk_add_f32 v[154:155], v[56:57], v[150:151] neg_lo:[0,1] neg_hi:[0,1]
	v_pk_add_f32 v[156:157], v[58:59], v[152:153] neg_lo:[0,1] neg_hi:[0,1]
	v_pk_add_f32 v[140:141], v[140:141], v[154:155]
	v_pk_add_f32 v[142:143], v[142:143], v[156:157]
	s_waitcnt vmcnt(17)
	v_cndmask_b32_e64 v150, v52, v44, s[94:95]
	v_cndmask_b32_e64 v151, v53, v45, s[94:95]
	v_cndmask_b32_e64 v152, v54, v46, s[94:95]
	v_cndmask_b32_e64 v153, v55, v47, s[94:95]
	v_pk_add_f32 v[154:155], v[60:61], v[150:151] neg_lo:[0,1] neg_hi:[0,1]
	v_pk_add_f32 v[156:157], v[62:63], v[152:153] neg_lo:[0,1] neg_hi:[0,1]
	v_pk_add_f32 v[140:141], v[140:141], v[154:155]
	v_pk_add_f32 v[142:143], v[142:143], v[156:157]
	s_waitcnt vmcnt(16)
	v_cndmask_b32_e64 v150, v56, v48, s[94:95]
	v_cndmask_b32_e64 v151, v57, v49, s[94:95]
	v_cndmask_b32_e64 v152, v58, v50, s[94:95]
	v_cndmask_b32_e64 v153, v59, v51, s[94:95]
	v_pk_add_f32 v[154:155], v[64:65], v[150:151] neg_lo:[0,1] neg_hi:[0,1]
	v_pk_add_f32 v[156:157], v[66:67], v[152:153] neg_lo:[0,1] neg_hi:[0,1]
	v_pk_add_f32 v[140:141], v[140:141], v[154:155]
	v_pk_add_f32 v[142:143], v[142:143], v[156:157]
	s_waitcnt vmcnt(15)
	v_cndmask_b32_e64 v150, v60, v52, s[94:95]
	v_cndmask_b32_e64 v151, v61, v53, s[94:95]
	v_cndmask_b32_e64 v152, v62, v54, s[94:95]
	v_cndmask_b32_e64 v153, v63, v55, s[94:95]
	v_pk_add_f32 v[154:155], v[68:69], v[150:151] neg_lo:[0,1] neg_hi:[0,1]
	v_pk_add_f32 v[156:157], v[70:71], v[152:153] neg_lo:[0,1] neg_hi:[0,1]
	v_pk_add_f32 v[140:141], v[140:141], v[154:155]
	v_pk_add_f32 v[142:143], v[142:143], v[156:157]
	s_waitcnt vmcnt(14)
; #define GAS __attribute__((address_space(1)))
; __device__ __forceinline__ unsigned pk2(float lo, float hi) { f32x2_t v = {lo, hi}; bf16x2_t b = __builtin_convertvector(v, bf16x2_t); return __builtin_bit_cast(unsigned, b); }
; #define U_LD(p) ({ const v2u w_ = *(const v2u*)(p); (f32x4){bflo(w_.x), bfhi(w_.x), bflo(w_.y), bfhi(w_.y)}; })
; __device__ __forceinline__ void p3_pool(Frame& F) {
;     ...
;                 if (s >= 0) n0 = U_LD(U + (mbase + s) * 512 + c0); else n0 = *(const f32x4*)(state_pool + ((size_t)b * 15 + (s + 15)) * 512 + c0);
;                 if (i >= w) { if (so >= 0) o0 = U_LD(U + (mbase + so) * 512 + c0); else o0 = *(const f32x4*)(state_pool + ((size_t)b * 15 + (so + 15)) * 512 + c0); }
;             }
;             S0 += n0 - o0;
;             if (i >= 15) {
;                 const int cnt = isP ? (w < s + 1 ? w : s + 1) : w; const float inv = 1.f / (float)cnt;
;                 const f32x4 d0 = S0 * inv - n0;
;                 v2u wv; wv.x = pk2(d0[0], d0[1]); wv.y = pk2(d0[2], d0[3]);
;                 *(GAS v2u*)(D + (size_t)(c0 >> 8) * ((size_t)MT * 256) + (mbase + s) * 256 + (c0 & 255)) = wv;
;             }
;             if (!isP && s >= -7 && s < 0) *(GAS f32x4*)(out + O_POOLS + ((size_t)b * 15 + (s + 7)) * 512 + c0) = n0;
	global_store_dwordx4 v37, v[72:75], s[92:93]
	v_cndmask_b32_e64 v150, v64, v56, s[94:95]
	v_cndmask_b32_e64 v151, v65, v57, s[94:95]
	v_cndmask_b32_e64 v152, v66, v58, s[94:95]
	v_cndmask_b32_e64 v153, v67, v59, s[94:95]
	v_pk_add_f32 v[154:155], v[72:73], v[150:151] neg_lo:[0,1] neg_hi:[0,1]
	v_pk_add_f32 v[156:157], v[74:75], v[152:153] neg_lo:[0,1] neg_hi:[0,1]
	v_pk_add_f32 v[140:141], v[140:141], v[154:155]
	v_pk_add_f32 v[142:143], v[142:143], v[156:157]
	s_waitcnt vmcnt(14)
	global_store_dwordx4 v37, v[76:79], s[92:93] offset:2048
	s_add_u32 s92, s92, 0x1000
	s_addc_u32 s93, s93, 0
	v_cndmask_b32_e64 v150, v68, v60, s[94:95]
	v_cndmask_b32_e64 v151, v69, v61, s[94:95]
	v_cndmask_b32_e64 v152, v70, v62, s[94:95]
	v_cndmask_b32_e64 v153, v71, v63, s[94:95]
	v_pk_add_f32 v[154:155], v[76:77], v[150:151] neg_lo:[0,1] neg_hi:[0,1]
	v_pk_add_f32 v[156:157], v[78:79], v[152:153] neg_lo:[0,1] neg_hi:[0,1]
	v_pk_add_f32 v[140:141], v[140:141], v[154:155]
	v_pk_add_f32 v[142:143], v[142:143], v[156:157]
	s_waitcnt vmcnt(14)
	global_store_dwordx4 v37, v[80:83], s[92:93]
	v_cndmask_b32_e64 v150, v72, v64, s[94:95]
	v_cndmask_b32_e64 v151, v73, v65, s[94:95]
	v_cndmask_b32_e64 v152, v74, v66, s[94:95]
	v_cndmask_b32_e64 v153, v75, v67, s[94:95]
	v_pk_add_f32 v[154:155], v[80:81], v[150:151] neg_lo:[0,1] neg_hi:[0,1]
	v_pk_add_f32 v[156:157], v[82:83], v[152:153] neg_lo:[0,1] neg_hi:[0,1]
	v_pk_add_f32 v[140:141], v[140:141], v[154:155]
	v_pk_add_f32 v[142:143], v[142:143], v[156:157]
	s_waitcnt vmcnt(14)
	global_store_dwordx4 v37, v[84:87], s[92:93] offset:2048
	s_add_u32 s92, s92, 0x1000
	s_addc_u32 s93, s93, 0
	v_cndmask_b32_e64 v150, v76, v68, s[94:95]
	v_cndmask_b32_e64 v151, v77, v69, s[94:95]
	v_cndmask_b32_e64 v152, v78, v70, s[94:95]
	v_cndmask_b32_e64 v153, v79, v71, s[94:95]
	v_pk_add_f32 v[154:155], v[84:85], v[150:151] neg_lo:[0,1] neg_hi:[0,1]
	v_pk_add_f32 v[156:157], v[86:87], v[152:153] neg_lo:[0,1] neg_hi:[0,1]
	v_pk_add_f32 v[140:141], v[140:141], v[154:155]
	v_pk_add_f32 v[142:143], v[142:143], v[156:157]
	s_waitcnt vmcnt(14)
	global_store_dwordx4 v37, v[88:91], s[92:93]
	v_cndmask_b32_e64 v150, v80, v72, s[94:95]
	v_cndmask_b32_e64 v151, v81, v73, s[94:95]
	v_cndmask_b32_e64 v152, v82, v74, s[94:95]
	v_cndmask_b32_e64 v153, v83, v75, s[94:95]
	v_pk_add_f32 v[154:155], v[88:89], v[150:151] neg_lo:[0,1] neg_hi:[0,1]
	v_pk_add_f32 v[156:157], v[90:91], v[152:153] neg_lo:[0,1] neg_hi:[0,1]
	v_pk_add_f32 v[140:141], v[140:141], v[154:155]
	v_pk_add_f32 v[142:143], v[142:143], v[156:157]
	s_waitcnt vmcnt(14)
	global_store_dwordx4 v37, v[92:95], s[92:93] offset:2048
	s_add_u32 s92, s92, 0x1000
	s_addc_u32 s93, s93, 0
	v_cndmask_b32_e64 v150, v84, v76, s[94:95]
	v_cndmask_b32_e64 v151, v85, v77, s[94:95]
	v_cndmask_b32_e64 v152, v86, v78, s[94:95]
	v_cndmask_b32_e64 v153, v87, v79, s[94:95]
	v_pk_add_f32 v[154:155], v[92:93], v[150:151] neg_lo:[0,1] neg_hi:[0,1]
	v_pk_add_f32 v[156:157], v[94:95], v[152:153] neg_lo:[0,1] neg_hi:[0,1]
	v_pk_add_f32 v[140:141], v[140:141], v[154:155]
	v_pk_add_f32 v[142:143], v[142:143], v[156:157]
	s_waitcnt vmcnt(14)
	global_store_dwordx4 v37, v[96:99], s[92:93]
	v_cndmask_b32_e64 v150, v88, v80, s[94:95]
	v_cndmask_b32_e64 v151, v89, v81, s[94:95]
	v_cndmask_b32_e64 v152, v90, v82, s[94:95]
	v_cndmask_b32_e64 v153, v91, v83, s[94:95]
	v_pk_add_f32 v[154:155], v[96:97], v[150:151] neg_lo:[0,1] neg_hi:[0,1]
	v_pk_add_f32 v[156:157], v[98:99], v[152:153] neg_lo:[0,1] neg_hi:[0,1]
	v_pk_add_f32 v[140:141], v[140:141], v[154:155]
	v_pk_add_f32 v[142:143], v[142:143], v[156:157]
	s_waitcnt vmcnt(14)
	v_lshlrev_b32_e32 v176, 16, v100
	v_and_b32_e32 v177, 0xffff0000, v100
	v_lshlrev_b32_e32 v178, 16, v101
	v_and_b32_e32 v179, 0xffff0000, v101
	v_cndmask_b32_e64 v150, v92, v84, s[94:95]
	v_cndmask_b32_e64 v151, v93, v85, s[94:95]
	v_cndmask_b32_e64 v152, v94, v86, s[94:95]
	v_cndmask_b32_e64 v153, v95, v87, s[94:95]
	v_pk_add_f32 v[154:155], v[176:177], v[150:151] neg_lo:[0,1] neg_hi:[0,1]
	v_pk_add_f32 v[156:157], v[178:179], v[152:153] neg_lo:[0,1] neg_hi:[0,1]
	v_pk_add_f32 v[140:141], v[140:141], v[154:155]
	v_pk_add_f32 v[142:143], v[142:143], v[156:157]
	v_pk_fma_f32 v[158:159], v[164:165], v[140:141], v[176:177] op_sel_hi:[0,1,1] neg_lo:[0,0,1] neg_hi:[0,0,1]
	v_pk_fma_f32 v[160:161], v[164:165], v[142:143], v[178:179] op_sel_hi:[0,1,1] neg_lo:[0,0,1] neg_hi:[0,0,1]
	v_cvt_pk_bf16_f32 v162, v158, v159
	v_cvt_pk_bf16_f32 v163, v160, v161
	global_store_dwordx2 v36, v[162:163], s[84:85]
	s_waitcnt vmcnt(14)
	v_lshlrev_b32_e32 v180, 16, v102
	v_and_b32_e32 v181, 0xffff0000, v102
	v_lshlrev_b32_e32 v182, 16, v103
	v_and_b32_e32 v183, 0xffff0000, v103
	v_cndmask_b32_e64 v150, v96, v88, s[94:95]
	v_cndmask_b32_e64 v151, v97, v89, s[94:95]
	v_cndmask_b32_e64 v152, v98, v90, s[94:95]
	v_cndmask_b32_e64 v153, v99, v91, s[94:95]
	v_pk_add_f32 v[154:155], v[180:181], v[150:151] neg_lo:[0,1] neg_hi:[0,1]
	v_pk_add_f32 v[156:157], v[182:183], v[152:153] neg_lo:[0,1] neg_hi:[0,1]
	v_pk_add_f32 v[140:141], v[140:141], v[154:155]
	v_pk_add_f32 v[142:143], v[142:143], v[156:157]
	v_pk_fma_f32 v[158:159], v[164:165], v[140:141], v[180:181] op_sel_hi:[0,1,1] neg_lo:[0,0,1] neg_hi:[0,0,1]
	v_pk_fma_f32 v[160:161], v[164:165], v[142:143], v[182:183] op_sel_hi:[0,1,1] neg_lo:[0,0,1] neg_hi:[0,0,1]
	v_cvt_pk_bf16_f32 v162, v158, v159
	v_cvt_pk_bf16_f32 v163, v160, v161
	global_store_dwordx2 v36, v[162:163], s[84:85] offset:512
	s_waitcnt vmcnt(14)
; #define GAS __attribute__((address_space(1)))
; __device__ __forceinline__ unsigned pk2(float lo, float hi) { f32x2_t v = {lo, hi}; bf16x2_t b = __builtin_convertvector(v, bf16x2_t); return __builtin_bit_cast(unsigned, b); }
; #define U_LD(p) ({ const v2u w_ = *(const v2u*)(p); (f32x4){bflo(w_.x), bfhi(w_.x), bflo(w_.y), bfhi(w_.y)}; })
; __device__ __forceinline__ void p3_pool(Frame& F) {
;     ...
;                 if (s >= 0) n0 = U_LD(U + (mbase + s) * 512 + c0); else n0 = *(const f32x4*)(state_pool + ((size_t)b * 15 + (s + 15)) * 512 + c0);
;                 if (i >= w) { if (so >= 0) o0 = U_LD(U + (mbase + so) * 512 + c0); else o0 = *(const f32x4*)(state_pool + ((size_t)b * 15 + (so + 15)) * 512 + c0); }
;             }
;             S0 += n0 - o0;
;             if (i >= 15) {
;                 const int cnt = isP ? (w < s + 1 ? w : s + 1) : w; const float inv = 1.f / (float)cnt;
;                 const f32x4 d0 = S0 * inv - n0;
;                 v2u wv; wv.x = pk2(d0[0], d0[1]); wv.y = pk2(d0[2], d0[3]);
;                 *(GAS v2u*)(D + (size_t)(c0 >> 8) * ((size_t)MT * 256) + (mbase + s) * 256 + (c0 & 255)) = wv;
;             }
	v_lshlrev_b32_e32 v184, 16, v104
	v_and_b32_e32 v185, 0xffff0000, v104
	v_lshlrev_b32_e32 v186, 16, v105
	v_and_b32_e32 v187, 0xffff0000, v105
	v_cndmask_b32_e64 v150, v176, v92, s[94:95]
	v_cndmask_b32_e64 v151, v177, v93, s[94:95]
	v_cndmask_b32_e64 v152, v178, v94, s[94:95]
	v_cndmask_b32_e64 v153, v179, v95, s[94:95]
	v_pk_add_f32 v[154:155], v[184:185], v[150:151] neg_lo:[0,1] neg_hi:[0,1]
	v_pk_add_f32 v[156:157], v[186:187], v[152:153] neg_lo:[0,1] neg_hi:[0,1]
	v_pk_add_f32 v[140:141], v[140:141], v[154:155]
	v_pk_add_f32 v[142:143], v[142:143], v[156:157]
	v_pk_fma_f32 v[158:159], v[164:165], v[140:141], v[184:185] op_sel_hi:[0,1,1] neg_lo:[0,0,1] neg_hi:[0,0,1]
	v_pk_fma_f32 v[160:161], v[164:165], v[142:143], v[186:187] op_sel_hi:[0,1,1] neg_lo:[0,0,1] neg_hi:[0,0,1]
	v_cvt_pk_bf16_f32 v162, v158, v159
	v_cvt_pk_bf16_f32 v163, v160, v161
	global_store_dwordx2 v36, v[162:163], s[84:85] offset:1024
	s_waitcnt vmcnt(14)
	v_lshlrev_b32_e32 v188, 16, v106
	v_and_b32_e32 v189, 0xffff0000, v106
	v_lshlrev_b32_e32 v190, 16, v107
	v_and_b32_e32 v191, 0xffff0000, v107
	v_cndmask_b32_e64 v150, v180, v96, s[94:95]
	v_cndmask_b32_e64 v151, v181, v97, s[94:95]
	v_cndmask_b32_e64 v152, v182, v98, s[94:95]
	v_cndmask_b32_e64 v153, v183, v99, s[94:95]
	v_pk_add_f32 v[154:155], v[188:189], v[150:151] neg_lo:[0,1] neg_hi:[0,1]
	v_pk_add_f32 v[156:157], v[190:191], v[152:153] neg_lo:[0,1] neg_hi:[0,1]
	v_pk_add_f32 v[140:141], v[140:141], v[154:155]
	v_pk_add_f32 v[142:143], v[142:143], v[156:157]
	v_pk_fma_f32 v[158:159], v[164:165], v[140:141], v[188:189] op_sel_hi:[0,1,1] neg_lo:[0,0,1] neg_hi:[0,0,1]
	v_pk_fma_f32 v[160:161], v[164:165], v[142:143], v[190:191] op_sel_hi:[0,1,1] neg_lo:[0,0,1] neg_hi:[0,0,1]
	v_cvt_pk_bf16_f32 v162, v158, v159
	v_cvt_pk_bf16_f32 v163, v160, v161
	global_store_dwordx2 v36, v[162:163], s[84:85] offset:1536
	s_waitcnt vmcnt(14)
	v_lshlrev_b32_e32 v192, 16, v108
	v_and_b32_e32 v193, 0xffff0000, v108
	v_lshlrev_b32_e32 v194, 16, v109
	v_and_b32_e32 v195, 0xffff0000, v109
	v_cndmask_b32_e64 v150, v184, v176, s[94:95]
	v_cndmask_b32_e64 v151, v185, v177, s[94:95]
	v_cndmask_b32_e64 v152, v186, v178, s[94:95]
	v_cndmask_b32_e64 v153, v187, v179, s[94:95]
	v_pk_add_f32 v[154:155], v[192:193], v[150:151] neg_lo:[0,1] neg_hi:[0,1]
	v_pk_add_f32 v[156:157], v[194:195], v[152:153] neg_lo:[0,1] neg_hi:[0,1]
	v_pk_add_f32 v[140:141], v[140:141], v[154:155]
	v_pk_add_f32 v[142:143], v[142:143], v[156:157]
	v_pk_fma_f32 v[158:159], v[164:165], v[140:141], v[192:193] op_sel_hi:[0,1,1] neg_lo:[0,0,1] neg_hi:[0,0,1]
	v_pk_fma_f32 v[160:161], v[164:165], v[142:143], v[194:195] op_sel_hi:[0,1,1] neg_lo:[0,0,1] neg_hi:[0,0,1]
	v_cvt_pk_bf16_f32 v162, v158, v159
	v_cvt_pk_bf16_f32 v163, v160, v161
	global_store_dwordx2 v36, v[162:163], s[84:85] offset:2048
	s_waitcnt vmcnt(14)
	v_lshlrev_b32_e32 v196, 16, v110
	v_and_b32_e32 v197, 0xffff0000, v110
	v_lshlrev_b32_e32 v198, 16, v111
	v_and_b32_e32 v199, 0xffff0000, v111
	v_cndmask_b32_e64 v150, v188, v180, s[94:95]
	v_cndmask_b32_e64 v151, v189, v181, s[94:95]
	v_cndmask_b32_e64 v152, v190, v182, s[94:95]
	v_cndmask_b32_e64 v153, v191, v183, s[94:95]
	v_pk_add_f32 v[154:155], v[196:197], v[150:151] neg_lo:[0,1] neg_hi:[0,1]
	v_pk_add_f32 v[156:157], v[198:199], v[152:153] neg_lo:[0,1] neg_hi:[0,1]
	v_pk_add_f32 v[140:141], v[140:141], v[154:155]
	v_pk_add_f32 v[142:143], v[142:143], v[156:157]
	v_pk_fma_f32 v[158:159], v[164:165], v[140:141], v[196:197] op_sel_hi:[0,1,1] neg_lo:[0,0,1] neg_hi:[0,0,1]
	v_pk_fma_f32 v[160:161], v[164:165], v[142:143], v[198:199] op_sel_hi:[0,1,1] neg_lo:[0,0,1] neg_hi:[0,0,1]
	v_cvt_pk_bf16_f32 v162, v158, v159
	v_cvt_pk_bf16_f32 v163, v160, v161
	global_store_dwordx2 v36, v[162:163], s[84:85] offset:2560
	s_waitcnt vmcnt(14)
	v_lshlrev_b32_e32 v200, 16, v112
	v_and_b32_e32 v201, 0xffff0000, v112
	v_lshlrev_b32_e32 v202, 16, v113
	v_and_b32_e32 v203, 0xffff0000, v113
	v_cndmask_b32_e64 v150, v192, v184, s[94:95]
	v_cndmask_b32_e64 v151, v193, v185, s[94:95]
	v_cndmask_b32_e64 v152, v194, v186, s[94:95]
	v_cndmask_b32_e64 v153, v195, v187, s[94:95]
	v_pk_add_f32 v[154:155], v[200:201], v[150:151] neg_lo:[0,1] neg_hi:[0,1]
	v_pk_add_f32 v[156:157], v[202:203], v[152:153] neg_lo:[0,1] neg_hi:[0,1]
	v_pk_add_f32 v[140:141], v[140:141], v[154:155]
	v_pk_add_f32 v[142:143], v[142:143], v[156:157]
	v_pk_fma_f32 v[158:159], v[164:165], v[140:141], v[200:201] op_sel_hi:[0,1,1] neg_lo:[0,0,1] neg_hi:[0,0,1]
	v_pk_fma_f32 v[160:161], v[164:165], v[142:143], v[202:203] op_sel_hi:[0,1,1] neg_lo:[0,0,1] neg_hi:[0,0,1]
	v_cvt_pk_bf16_f32 v162, v158, v159
	v_cvt_pk_bf16_f32 v163, v160, v161
	global_store_dwordx2 v36, v[162:163], s[84:85] offset:3072
	s_waitcnt vmcnt(14)
	v_lshlrev_b32_e32 v204, 16, v114
	v_and_b32_e32 v205, 0xffff0000, v114
	v_lshlrev_b32_e32 v206, 16, v115
	v_and_b32_e32 v207, 0xffff0000, v115
	v_cndmask_b32_e64 v150, v196, v188, s[94:95]
	v_cndmask_b32_e64 v151, v197, v189, s[94:95]
	v_cndmask_b32_e64 v152, v198, v190, s[94:95]
	v_cndmask_b32_e64 v153, v199, v191, s[94:95]
	v_pk_add_f32 v[154:155], v[204:205], v[150:151] neg_lo:[0,1] neg_hi:[0,1]
	v_pk_add_f32 v[156:157], v[206:207], v[152:153] neg_lo:[0,1] neg_hi:[0,1]
	v_pk_add_f32 v[140:141], v[140:141], v[154:155]
	v_pk_add_f32 v[142:143], v[142:143], v[156:157]
	v_pk_fma_f32 v[158:159], v[164:165], v[140:141], v[204:205] op_sel_hi:[0,1,1] neg_lo:[0,0,1] neg_hi:[0,0,1]
	v_pk_fma_f32 v[160:161], v[164:165], v[142:143], v[206:207] op_sel_hi:[0,1,1] neg_lo:[0,0,1] neg_hi:[0,0,1]
	v_cvt_pk_bf16_f32 v162, v158, v159
	v_cvt_pk_bf16_f32 v163, v160, v161
	global_store_dwordx2 v36, v[162:163], s[84:85] offset:3584
	s_branch .LBB0_515

;     static __device__ __forceinline__ f32x4 ldb(const void* base, size_t idx) { if (MODE == 0) return *(const f32x4*)((const float*)base + idx); const u32x2 w = *(const u32x2*)((const bf16_t*)base + idx); return (f32x4){bflo(w.x), bfhi(w.x), bflo(w.y), bfhi(w.y)}; }
;     __device__ __forceinline__ void operator()(const f32x4 (&acc)[2][2][4][2], const Unit& u, int wr, int wc, int fr, int fq) const {
;     ...
;         const float* gp0 = gate + (size_t)((u.pm * BM) >> 11) * NMOD + col0;
;         f32x4 gt[2][2];
; #pragma unroll
;         for (int bj = 0; bj < 2; ++bj)
; #pragma unroll
;             for (int n = 0; n < 2; ++n) gt[bj][n] = *(const f32x4*)(gp0 + bj * HALF + n * 16);
; #pragma unroll
;         for (int ai = 0; ai < 2; ++ai)
; #pragma unroll
;           for (int mp = 0; mp < 2; ++mp) { f32x4 bb[2][2][2];
; #pragma unroll
;             for (int mm = 0; mm < 2; ++mm) { const size_t bi = (size_t)(row0 + ai * HALF + (2 * mp + mm) * 16) * DM + col0;
; #pragma unroll
;                 for (int bj = 0; bj < 2; ++bj)
; #pragma unroll
;                     for (int n = 0; n < 2; ++n) bb[mm][bj][n] = ldb(baseP, bi + bj * HALF + n * 16); }
; #pragma unroll
;             for (int mm = 0; mm < 2; ++mm) { const int m = 2 * mp + mm; float s = 0.f;
; #pragma unroll
;                 for (int bj = 0; bj < 2; ++bj)
; #pragma unroll
;                     for (int n = 0; n < 2; ++n) { const f32x4 x = bb[mm][bj][n] + gt[bj][n] * acc[ai][bj][m][n]; s += (x[0] * x[0] + x[1] * x[1]) + (x[2] * x[2] + x[3] * x[3]); }
;                 s += __shfl_xor(s, 16); s += __shfl_xor(s, 32);
;                 if (fq == 0) P[(ai * HALF + wr * 64 + m * 16 + fr) * 4 + wc] = s; }
;             asm volatile("" ::: "memory"); }
.LBB0_1602:
	s_lshl_b32 s41, s14, 8
	v_mbcnt_lo_u32_b32 v156, -1, 0
	v_mbcnt_hi_u32_b32 v156, -1, v156
	s_add_i32 s8, s41, s29
	v_and_b32_e32 v190, 15, v156
	v_or_b32_e32 v174, s8, v190
	s_lshl_b32 s8, s68, 8
	v_readlane_b32 s9, v237, 10
	v_ashrrev_i32_e32 v191, 4, v156
	s_or_b32 s8, s8, s9
	v_lshl_add_u32 v176, v191, 2, s8
	s_mov_b64 s[12:13], -1
	s_cmp_lt_i32 s40, 0
	v_ashrrev_i32_e32 v177, 31, v176
	s_cbranch_scc0 .LBB0_1644
	v_ashrrev_i32_e32 v175, 31, v174
	s_ashr_i32 s8, s14, 3
	s_mul_hi_i32 s9, s8, 0x6000
	s_mulk_i32 s8, 0x6000
	s_add_u32 s12, s26, s8
	s_addc_u32 s13, s27, s9
	v_lshl_add_u64 v[146:147], v[176:177], 2, s[12:13]
	global_load_dwordx4 v[142:145], v[146:147], off
	global_load_dwordx4 v[138:141], v[146:147], off offset:64
	global_load_dwordx4 v[134:137], v[146:147], off offset:512
	global_load_dwordx4 v[130:133], v[146:147], off offset:576
	v_lshl_add_u64 v[146:147], v[176:177], 1, s[42:43]
	v_lshlrev_b64 v[148:149], 11, v[174:175]
	v_lshl_add_u64 v[148:149], v[146:147], 0, v[148:149]
	s_mov_b64 s[24:25], 0x8000
	s_mov_b64 s[70:71], 0x28000
	global_load_dwordx2 v[150:151], v[148:149], off nt
	global_load_dwordx2 v[152:153], v[148:149], off offset:32 nt
	global_load_dwordx2 v[154:155], v[148:149], off offset:256 nt
	global_load_dwordx2 v[158:159], v[148:149], off offset:288 nt
	v_lshl_add_u64 v[148:149], v[148:149], 0, s[24:25]
	global_load_dwordx2 v[160:161], v[148:149], off nt
	global_load_dwordx2 v[178:179], v[148:149], off offset:32 nt
	global_load_dwordx2 v[180:181], v[148:149], off offset:256 nt
	global_load_dwordx2 v[192:193], v[148:149], off offset:288 nt
	v_lshl_add_u64 v[148:149], v[148:149], 0, s[24:25]
	global_load_dwordx2 v[194:195], v[148:149], off nt
	global_load_dwordx2 v[196:197], v[148:149], off offset:32 nt
	global_load_dwordx2 v[198:199], v[148:149], off offset:256 nt
	global_load_dwordx2 v[200:201], v[148:149], off offset:288 nt
	v_lshl_add_u64 v[148:149], v[148:149], 0, s[24:25]
	global_load_dwordx2 v[202:203], v[148:149], off nt
	global_load_dwordx2 v[204:205], v[148:149], off offset:32 nt
	global_load_dwordx2 v[206:207], v[148:149], off offset:256 nt
	global_load_dwordx2 v[210:211], v[148:149], off offset:288 nt
	v_lshl_add_u64 v[148:149], v[148:149], 0, s[70:71]
	global_load_dwordx2 v[212:213], v[148:149], off nt
	global_load_dwordx2 v[214:215], v[148:149], off offset:32 nt
	global_load_dwordx2 v[216:217], v[148:149], off offset:256 nt
	global_load_dwordx2 v[218:219], v[148:149], off offset:288 nt
	v_lshl_add_u64 v[148:149], v[148:149], 0, s[24:25]
	global_load_dwordx2 v[220:221], v[148:149], off nt
	global_load_dwordx2 v[222:223], v[148:149], off offset:32 nt
	global_load_dwordx2 v[226:227], v[148:149], off offset:256 nt
	global_load_dwordx2 v[228:229], v[148:149], off offset:288 nt
	v_lshl_add_u64 v[148:149], v[148:149], 0, s[24:25]
	global_load_dwordx2 v[230:231], v[148:149], off nt
	global_load_dwordx2 v[232:233], v[148:149], off offset:32 nt
	global_load_dwordx2 v[234:235], v[148:149], off offset:256 nt
	global_load_dwordx2 v[238:239], v[148:149], off offset:288 nt
	v_lshl_add_u64 v[148:149], v[148:149], 0, s[24:25]
	global_load_dwordx2 v[240:241], v[148:149], off nt
	global_load_dwordx2 v[242:243], v[148:149], off offset:32 nt
	global_load_dwordx2 v[244:245], v[148:149], off offset:256 nt
	global_load_dwordx2 v[246:247], v[148:149], off offset:288 nt
	v_xor_b32_e32 v157, 16, v156
	v_xor_b32_e32 v175, 32, v156
	v_or_b32_e32 v183, s29, v190
	v_lshlrev_b32_e32 v157, 2, v157
	v_lshlrev_b32_e32 v175, 2, v175
	v_lshl_add_u32 v182, v183, 4, s96
	v_cmp_gt_u32_e64 s[12:13], 16, v156
	s_waitcnt vmcnt(28)
	v_lshlrev_b32_e32 v146, 16, v150
	v_and_b32_e32 v147, 0xffff0000, v150
	v_lshlrev_b32_e32 v150, 16, v151
	v_and_b32_e32 v151, 0xffff0000, v151
	v_pk_fma_f32 v[126:127], v[126:127], v[142:143], v[146:147]
	v_pk_fma_f32 v[128:129], v[128:129], v[144:145], v[150:151]
	v_pk_mul_f32 v[150:151], v[126:127], v[126:127]
	v_pk_fma_f32 v[150:151], v[128:129], v[128:129], v[150:151]
	v_lshlrev_b32_e32 v146, 16, v152
	v_and_b32_e32 v147, 0xffff0000, v152
	v_lshlrev_b32_e32 v152, 16, v153
	v_and_b32_e32 v153, 0xffff0000, v153
	v_pk_fma_f32 v[122:123], v[122:123], v[138:139], v[146:147]
	v_pk_fma_f32 v[124:125], v[124:125], v[140:141], v[152:153]
	v_pk_fma_f32 v[150:151], v[122:123], v[122:123], v[150:151]
	v_pk_fma_f32 v[150:151], v[124:125], v[124:125], v[150:151]
	v_lshlrev_b32_e32 v146, 16, v154
	v_and_b32_e32 v147, 0xffff0000, v154
	v_lshlrev_b32_e32 v154, 16, v155
	v_and_b32_e32 v155, 0xffff0000, v155
	v_pk_fma_f32 v[110:111], v[110:111], v[134:135], v[146:147]
	v_pk_fma_f32 v[112:113], v[112:113], v[136:137], v[154:155]
	v_pk_fma_f32 v[150:151], v[110:111], v[110:111], v[150:151]
	v_pk_fma_f32 v[150:151], v[112:113], v[112:113], v[150:151]
	v_lshlrev_b32_e32 v146, 16, v158
	v_and_b32_e32 v147, 0xffff0000, v158
	v_lshlrev_b32_e32 v158, 16, v159
	v_and_b32_e32 v159, 0xffff0000, v159
	v_pk_fma_f32 v[102:103], v[102:103], v[130:131], v[146:147]
	v_pk_fma_f32 v[104:105], v[104:105], v[132:133], v[158:159]
	v_pk_fma_f32 v[150:151], v[102:103], v[102:103], v[150:151]
	v_pk_fma_f32 v[150:151], v[104:105], v[104:105], v[150:151]
	v_add_f32_e32 v150, v150, v151
	s_waitcnt vmcnt(24)
;     static __device__ __forceinline__ f32x4 ldb(const void* base, size_t idx) { if (MODE == 0) return *(const f32x4*)((const float*)base + idx); const u32x2 w = *(const u32x2*)((const bf16_t*)base + idx); return (f32x4){bflo(w.x), bfhi(w.x), bflo(w.y), bfhi(w.y)}; }
;     __device__ __forceinline__ void operator()(const f32x4 (&acc)[2][2][4][2], const Unit& u, int wr, int wc, int fr, int fq) const {
;     ...
;         for (int ai = 0; ai < 2; ++ai)
; #pragma unroll
;           for (int mp = 0; mp < 2; ++mp) { f32x4 bb[2][2][2];
; #pragma unroll
;             for (int mm = 0; mm < 2; ++mm) { const size_t bi = (size_t)(row0 + ai * HALF + (2 * mp + mm) * 16) * DM + col0;
; #pragma unroll
;                 for (int bj = 0; bj < 2; ++bj)
; #pragma unroll
;                     for (int n = 0; n < 2; ++n) bb[mm][bj][n] = ldb(baseP, bi + bj * HALF + n * 16); }
; #pragma unroll
;             for (int mm = 0; mm < 2; ++mm) { const int m = 2 * mp + mm; float s = 0.f;
; #pragma unroll
;                 for (int bj = 0; bj < 2; ++bj)
; #pragma unroll
;                     for (int n = 0; n < 2; ++n) { const f32x4 x = bb[mm][bj][n] + gt[bj][n] * acc[ai][bj][m][n]; s += (x[0] * x[0] + x[1] * x[1]) + (x[2] * x[2] + x[3] * x[3]); }
;                 s += __shfl_xor(s, 16); s += __shfl_xor(s, 32);
;                 if (fq == 0) P[(ai * HALF + wr * 64 + m * 16 + fr) * 4 + wc] = s; }
;             asm volatile("" ::: "memory"); }
	v_lshlrev_b32_e32 v146, 16, v160
	v_and_b32_e32 v147, 0xffff0000, v160
	v_lshlrev_b32_e32 v160, 16, v161
	v_and_b32_e32 v161, 0xffff0000, v161
	v_pk_fma_f32 v[118:119], v[118:119], v[142:143], v[146:147]
	v_pk_fma_f32 v[120:121], v[120:121], v[144:145], v[160:161]
	v_pk_mul_f32 v[160:161], v[118:119], v[118:119]
	v_pk_fma_f32 v[160:161], v[120:121], v[120:121], v[160:161]
	v_lshlrev_b32_e32 v146, 16, v178
	v_and_b32_e32 v147, 0xffff0000, v178
	v_lshlrev_b32_e32 v178, 16, v179
	v_and_b32_e32 v179, 0xffff0000, v179
	v_pk_fma_f32 v[114:115], v[114:115], v[138:139], v[146:147]
	v_pk_fma_f32 v[116:117], v[116:117], v[140:141], v[178:179]
	v_pk_fma_f32 v[160:161], v[114:115], v[114:115], v[160:161]
	v_pk_fma_f32 v[160:161], v[116:117], v[116:117], v[160:161]
	v_lshlrev_b32_e32 v146, 16, v180
	v_and_b32_e32 v147, 0xffff0000, v180
	v_lshlrev_b32_e32 v180, 16, v181
	v_and_b32_e32 v181, 0xffff0000, v181
	v_pk_fma_f32 v[94:95], v[94:95], v[134:135], v[146:147]
	v_pk_fma_f32 v[96:97], v[96:97], v[136:137], v[180:181]
	v_pk_fma_f32 v[160:161], v[94:95], v[94:95], v[160:161]
	v_pk_fma_f32 v[160:161], v[96:97], v[96:97], v[160:161]
	v_lshlrev_b32_e32 v146, 16, v192
	v_and_b32_e32 v147, 0xffff0000, v192
	v_lshlrev_b32_e32 v192, 16, v193
	v_and_b32_e32 v193, 0xffff0000, v193
	v_pk_fma_f32 v[86:87], v[86:87], v[130:131], v[146:147]
	v_pk_fma_f32 v[88:89], v[88:89], v[132:133], v[192:193]
	v_pk_fma_f32 v[160:161], v[86:87], v[86:87], v[160:161]
	v_pk_fma_f32 v[160:161], v[88:89], v[88:89], v[160:161]
	v_add_f32_e32 v160, v160, v161
	s_waitcnt vmcnt(20)
	v_lshlrev_b32_e32 v146, 16, v194
	v_and_b32_e32 v147, 0xffff0000, v194
	v_lshlrev_b32_e32 v194, 16, v195
	v_and_b32_e32 v195, 0xffff0000, v195
	v_pk_fma_f32 v[106:107], v[106:107], v[142:143], v[146:147]
	v_pk_fma_f32 v[108:109], v[108:109], v[144:145], v[194:195]
	v_pk_mul_f32 v[194:195], v[106:107], v[106:107]
	v_pk_fma_f32 v[194:195], v[108:109], v[108:109], v[194:195]
	v_lshlrev_b32_e32 v146, 16, v196
	v_and_b32_e32 v147, 0xffff0000, v196
	v_lshlrev_b32_e32 v196, 16, v197
	v_and_b32_e32 v197, 0xffff0000, v197
	v_pk_fma_f32 v[98:99], v[98:99], v[138:139], v[146:147]
	v_pk_fma_f32 v[100:101], v[100:101], v[140:141], v[196:197]
	v_pk_fma_f32 v[194:195], v[98:99], v[98:99], v[194:195]
	v_pk_fma_f32 v[194:195], v[100:101], v[100:101], v[194:195]
	v_lshlrev_b32_e32 v146, 16, v198
	v_and_b32_e32 v147, 0xffff0000, v198
	v_lshlrev_b32_e32 v198, 16, v199
	v_and_b32_e32 v199, 0xffff0000, v199
	v_pk_fma_f32 v[78:79], v[78:79], v[134:135], v[146:147]
	v_pk_fma_f32 v[80:81], v[80:81], v[136:137], v[198:199]
	v_pk_fma_f32 v[194:195], v[78:79], v[78:79], v[194:195]
	v_pk_fma_f32 v[194:195], v[80:81], v[80:81], v[194:195]
	v_lshlrev_b32_e32 v146, 16, v200
	v_and_b32_e32 v147, 0xffff0000, v200
	v_lshlrev_b32_e32 v200, 16, v201
	v_and_b32_e32 v201, 0xffff0000, v201
	v_pk_fma_f32 v[74:75], v[74:75], v[130:131], v[146:147]
	v_pk_fma_f32 v[76:77], v[76:77], v[132:133], v[200:201]
	v_pk_fma_f32 v[194:195], v[74:75], v[74:75], v[194:195]
	v_pk_fma_f32 v[194:195], v[76:77], v[76:77], v[194:195]
	v_add_f32_e32 v194, v194, v195
	s_waitcnt vmcnt(16)
	v_lshlrev_b32_e32 v146, 16, v202
	v_and_b32_e32 v147, 0xffff0000, v202
	v_lshlrev_b32_e32 v202, 16, v203
	v_and_b32_e32 v203, 0xffff0000, v203
	v_pk_fma_f32 v[90:91], v[90:91], v[142:143], v[146:147]
	v_pk_fma_f32 v[92:93], v[92:93], v[144:145], v[202:203]
	v_pk_mul_f32 v[202:203], v[90:91], v[90:91]
	v_pk_fma_f32 v[202:203], v[92:93], v[92:93], v[202:203]
	v_lshlrev_b32_e32 v146, 16, v204
	v_and_b32_e32 v147, 0xffff0000, v204
	v_lshlrev_b32_e32 v204, 16, v205
	v_and_b32_e32 v205, 0xffff0000, v205
	v_pk_fma_f32 v[82:83], v[82:83], v[138:139], v[146:147]
	v_pk_fma_f32 v[84:85], v[84:85], v[140:141], v[204:205]
	v_pk_fma_f32 v[202:203], v[82:83], v[82:83], v[202:203]
	v_pk_fma_f32 v[202:203], v[84:85], v[84:85], v[202:203]
	v_lshlrev_b32_e32 v146, 16, v206
	v_and_b32_e32 v147, 0xffff0000, v206
	v_lshlrev_b32_e32 v206, 16, v207
	v_and_b32_e32 v207, 0xffff0000, v207
	v_pk_fma_f32 v[70:71], v[70:71], v[134:135], v[146:147]
	v_pk_fma_f32 v[72:73], v[72:73], v[136:137], v[206:207]
	v_pk_fma_f32 v[202:203], v[70:71], v[70:71], v[202:203]
	v_pk_fma_f32 v[202:203], v[72:73], v[72:73], v[202:203]
	v_lshlrev_b32_e32 v146, 16, v210
	v_and_b32_e32 v147, 0xffff0000, v210
	v_lshlrev_b32_e32 v210, 16, v211
	v_and_b32_e32 v211, 0xffff0000, v211
	v_pk_fma_f32 v[66:67], v[66:67], v[130:131], v[146:147]
	v_pk_fma_f32 v[68:69], v[68:69], v[132:133], v[210:211]
	v_pk_fma_f32 v[202:203], v[66:67], v[66:67], v[202:203]
	v_pk_fma_f32 v[202:203], v[68:69], v[68:69], v[202:203]
	v_add_f32_e32 v202, v202, v203
	s_waitcnt vmcnt(12)
	v_lshlrev_b32_e32 v146, 16, v212
	v_and_b32_e32 v147, 0xffff0000, v212
	v_lshlrev_b32_e32 v212, 16, v213
	v_and_b32_e32 v213, 0xffff0000, v213
	v_pk_fma_f32 v[62:63], v[62:63], v[142:143], v[146:147]
	v_pk_fma_f32 v[64:65], v[64:65], v[144:145], v[212:213]
	v_pk_mul_f32 v[212:213], v[62:63], v[62:63]
	v_pk_fma_f32 v[212:213], v[64:65], v[64:65], v[212:213]
	v_lshlrev_b32_e32 v146, 16, v214
	v_and_b32_e32 v147, 0xffff0000, v214
	v_lshlrev_b32_e32 v214, 16, v215
	v_and_b32_e32 v215, 0xffff0000, v215
	v_pk_fma_f32 v[58:59], v[58:59], v[138:139], v[146:147]
	v_pk_fma_f32 v[60:61], v[60:61], v[140:141], v[214:215]
	v_pk_fma_f32 v[212:213], v[58:59], v[58:59], v[212:213]
	v_pk_fma_f32 v[212:213], v[60:61], v[60:61], v[212:213]
	v_lshlrev_b32_e32 v146, 16, v216
	v_and_b32_e32 v147, 0xffff0000, v216
	v_lshlrev_b32_e32 v216, 16, v217
	v_and_b32_e32 v217, 0xffff0000, v217
	v_pk_fma_f32 v[46:47], v[46:47], v[134:135], v[146:147]
	v_pk_fma_f32 v[48:49], v[48:49], v[136:137], v[216:217]
	v_pk_fma_f32 v[212:213], v[46:47], v[46:47], v[212:213]
	v_pk_fma_f32 v[212:213], v[48:49], v[48:49], v[212:213]
	v_lshlrev_b32_e32 v146, 16, v218
	v_and_b32_e32 v147, 0xffff0000, v218
	v_lshlrev_b32_e32 v218, 16, v219
	v_and_b32_e32 v219, 0xffff0000, v219
	v_pk_fma_f32 v[38:39], v[38:39], v[130:131], v[146:147]
	v_pk_fma_f32 v[40:41], v[40:41], v[132:133], v[218:219]
	v_pk_fma_f32 v[212:213], v[38:39], v[38:39], v[212:213]
	v_pk_fma_f32 v[212:213], v[40:41], v[40:41], v[212:213]
	v_add_f32_e32 v212, v212, v213
	s_waitcnt vmcnt(8)
; #define PG8_LAS __attribute__((address_space(3)))
;     __device__ __forceinline__ void operator()(const f32x4 (&acc)[2][2][4][2], const Unit& u, int wr, int wc, int fr, int fq) const {
;     ...
;             for (int mm = 0; mm < 2; ++mm) { const int m = 2 * mp + mm; float s = 0.f;
; #pragma unroll
;                 for (int bj = 0; bj < 2; ++bj)
; #pragma unroll
;                     for (int n = 0; n < 2; ++n) { const f32x4 x = bb[mm][bj][n] + gt[bj][n] * acc[ai][bj][m][n]; s += (x[0] * x[0] + x[1] * x[1]) + (x[2] * x[2] + x[3] * x[3]); }
;                 s += __shfl_xor(s, 16); s += __shfl_xor(s, 32);
;                 if (fq == 0) P[(ai * HALF + wr * 64 + m * 16 + fr) * 4 + wc] = s; }
;             asm volatile("" ::: "memory"); }
;         asm volatile("s_waitcnt lgkmcnt(0)" ::: "memory"); __builtin_amdgcn_s_barrier(); asm volatile("" ::: "memory");
;         const int tid = (wr * 4 + wc) * 64 + fq * 16 + fr;
;         if (tid < 256) { const f32x4 p = *(const PG8_LAS f32x4*)(P + tid * 4); __hip_atomic_store(ssq + (size_t)(u.pm * BM + tid) * 4 + u.pn, (p[0] + p[1]) + (p[2] + p[3]), __ATOMIC_RELAXED, __HIP_MEMORY_SCOPE_AGENT); }
	v_lshlrev_b32_e32 v146, 16, v220
	v_and_b32_e32 v147, 0xffff0000, v220
	v_lshlrev_b32_e32 v220, 16, v221
	v_and_b32_e32 v221, 0xffff0000, v221
	v_pk_fma_f32 v[54:55], v[54:55], v[142:143], v[146:147]
	v_pk_fma_f32 v[56:57], v[56:57], v[144:145], v[220:221]
	v_pk_mul_f32 v[220:221], v[54:55], v[54:55]
	v_pk_fma_f32 v[220:221], v[56:57], v[56:57], v[220:221]
	v_lshlrev_b32_e32 v146, 16, v222
	v_and_b32_e32 v147, 0xffff0000, v222
	v_lshlrev_b32_e32 v222, 16, v223
	v_and_b32_e32 v223, 0xffff0000, v223
	v_pk_fma_f32 v[50:51], v[50:51], v[138:139], v[146:147]
	v_pk_fma_f32 v[52:53], v[52:53], v[140:141], v[222:223]
	v_pk_fma_f32 v[220:221], v[50:51], v[50:51], v[220:221]
	v_pk_fma_f32 v[220:221], v[52:53], v[52:53], v[220:221]
	v_lshlrev_b32_e32 v146, 16, v226
	v_and_b32_e32 v147, 0xffff0000, v226
	v_lshlrev_b32_e32 v226, 16, v227
	v_and_b32_e32 v227, 0xffff0000, v227
	v_pk_fma_f32 v[30:31], v[30:31], v[134:135], v[146:147]
	v_pk_fma_f32 v[32:33], v[32:33], v[136:137], v[226:227]
	v_pk_fma_f32 v[220:221], v[30:31], v[30:31], v[220:221]
	v_pk_fma_f32 v[220:221], v[32:33], v[32:33], v[220:221]
	v_lshlrev_b32_e32 v146, 16, v228
	v_and_b32_e32 v147, 0xffff0000, v228
	v_lshlrev_b32_e32 v228, 16, v229
	v_and_b32_e32 v229, 0xffff0000, v229
	v_pk_fma_f32 v[22:23], v[22:23], v[130:131], v[146:147]
	v_pk_fma_f32 v[24:25], v[24:25], v[132:133], v[228:229]
	v_pk_fma_f32 v[220:221], v[22:23], v[22:23], v[220:221]
	v_pk_fma_f32 v[220:221], v[24:25], v[24:25], v[220:221]
	v_add_f32_e32 v220, v220, v221
	s_waitcnt vmcnt(4)
	v_lshlrev_b32_e32 v146, 16, v230
	v_and_b32_e32 v147, 0xffff0000, v230
	v_lshlrev_b32_e32 v230, 16, v231
	v_and_b32_e32 v231, 0xffff0000, v231
	v_pk_fma_f32 v[42:43], v[42:43], v[142:143], v[146:147]
	v_pk_fma_f32 v[44:45], v[44:45], v[144:145], v[230:231]
	v_pk_mul_f32 v[230:231], v[42:43], v[42:43]
	v_pk_fma_f32 v[230:231], v[44:45], v[44:45], v[230:231]
	v_lshlrev_b32_e32 v146, 16, v232
	v_and_b32_e32 v147, 0xffff0000, v232
	v_lshlrev_b32_e32 v232, 16, v233
	v_and_b32_e32 v233, 0xffff0000, v233
	v_pk_fma_f32 v[34:35], v[34:35], v[138:139], v[146:147]
	v_pk_fma_f32 v[36:37], v[36:37], v[140:141], v[232:233]
	v_pk_fma_f32 v[230:231], v[34:35], v[34:35], v[230:231]
	v_pk_fma_f32 v[230:231], v[36:37], v[36:37], v[230:231]
	v_lshlrev_b32_e32 v146, 16, v234
	v_and_b32_e32 v147, 0xffff0000, v234
	v_lshlrev_b32_e32 v234, 16, v235
	v_and_b32_e32 v235, 0xffff0000, v235
	v_pk_fma_f32 v[14:15], v[14:15], v[134:135], v[146:147]
	v_pk_fma_f32 v[16:17], v[16:17], v[136:137], v[234:235]
	v_pk_fma_f32 v[230:231], v[14:15], v[14:15], v[230:231]
	v_pk_fma_f32 v[230:231], v[16:17], v[16:17], v[230:231]
	v_lshlrev_b32_e32 v146, 16, v238
	v_and_b32_e32 v147, 0xffff0000, v238
	v_lshlrev_b32_e32 v238, 16, v239
	v_and_b32_e32 v239, 0xffff0000, v239
	v_pk_fma_f32 v[10:11], v[10:11], v[130:131], v[146:147]
	v_pk_fma_f32 v[12:13], v[12:13], v[132:133], v[238:239]
	v_pk_fma_f32 v[230:231], v[10:11], v[10:11], v[230:231]
	v_pk_fma_f32 v[230:231], v[12:13], v[12:13], v[230:231]
	v_add_f32_e32 v230, v230, v231
	s_waitcnt vmcnt(0)
	v_lshlrev_b32_e32 v146, 16, v240
	v_and_b32_e32 v147, 0xffff0000, v240
	v_lshlrev_b32_e32 v240, 16, v241
	v_and_b32_e32 v241, 0xffff0000, v241
	v_pk_fma_f32 v[26:27], v[26:27], v[142:143], v[146:147]
	v_pk_fma_f32 v[28:29], v[28:29], v[144:145], v[240:241]
	v_pk_mul_f32 v[240:241], v[26:27], v[26:27]
	v_pk_fma_f32 v[240:241], v[28:29], v[28:29], v[240:241]
	v_lshlrev_b32_e32 v146, 16, v242
	v_and_b32_e32 v147, 0xffff0000, v242
	v_lshlrev_b32_e32 v242, 16, v243
	v_and_b32_e32 v243, 0xffff0000, v243
	v_pk_fma_f32 v[18:19], v[18:19], v[138:139], v[146:147]
	v_pk_fma_f32 v[20:21], v[20:21], v[140:141], v[242:243]
	v_pk_fma_f32 v[240:241], v[18:19], v[18:19], v[240:241]
	v_pk_fma_f32 v[240:241], v[20:21], v[20:21], v[240:241]
	v_lshlrev_b32_e32 v146, 16, v244
	v_and_b32_e32 v147, 0xffff0000, v244
	v_lshlrev_b32_e32 v244, 16, v245
	v_and_b32_e32 v245, 0xffff0000, v245
	v_pk_fma_f32 v[6:7], v[6:7], v[134:135], v[146:147]
	v_pk_fma_f32 v[8:9], v[8:9], v[136:137], v[244:245]
	v_pk_fma_f32 v[240:241], v[6:7], v[6:7], v[240:241]
	v_pk_fma_f32 v[240:241], v[8:9], v[8:9], v[240:241]
	v_lshlrev_b32_e32 v146, 16, v246
	v_and_b32_e32 v147, 0xffff0000, v246
	v_lshlrev_b32_e32 v246, 16, v247
	v_and_b32_e32 v247, 0xffff0000, v247
	v_pk_fma_f32 v[2:3], v[2:3], v[130:131], v[146:147]
	v_pk_fma_f32 v[4:5], v[4:5], v[132:133], v[246:247]
	v_pk_fma_f32 v[240:241], v[2:3], v[2:3], v[240:241]
	v_pk_fma_f32 v[240:241], v[4:5], v[4:5], v[240:241]
	v_add_f32_e32 v240, v240, v241
	ds_bpermute_b32 v152, v157, v150
	ds_bpermute_b32 v178, v157, v160
	ds_bpermute_b32 v196, v157, v194
	ds_bpermute_b32 v204, v157, v202
	ds_bpermute_b32 v214, v157, v212
	ds_bpermute_b32 v222, v157, v220
	ds_bpermute_b32 v232, v157, v230
	ds_bpermute_b32 v242, v157, v240
	s_waitcnt lgkmcnt(0)
	v_add_f32_e32 v150, v150, v152
	v_add_f32_e32 v160, v160, v178
	v_add_f32_e32 v194, v194, v196
	v_add_f32_e32 v202, v202, v204
	v_add_f32_e32 v212, v212, v214
	v_add_f32_e32 v220, v220, v222
	v_add_f32_e32 v230, v230, v232
	v_add_f32_e32 v240, v240, v242
	ds_bpermute_b32 v152, v175, v150
	ds_bpermute_b32 v178, v175, v160
	ds_bpermute_b32 v196, v175, v194
	ds_bpermute_b32 v204, v175, v202
	ds_bpermute_b32 v214, v175, v212
	ds_bpermute_b32 v222, v175, v220
	ds_bpermute_b32 v232, v175, v230
	ds_bpermute_b32 v242, v175, v240
	s_waitcnt lgkmcnt(0)
	v_add_f32_e32 v150, v150, v152
	v_add_f32_e32 v160, v160, v178
	v_add_f32_e32 v194, v194, v196
	v_add_f32_e32 v202, v202, v204
	v_add_f32_e32 v212, v212, v214
	v_add_f32_e32 v220, v220, v222
	v_add_f32_e32 v230, v230, v232
	v_add_f32_e32 v240, v240, v242
	s_and_saveexec_b64 s[70:71], s[12:13]
	ds_write_b32 v182, v150
	ds_write_b32 v182, v160 offset:256
	ds_write_b32 v182, v194 offset:512
	ds_write_b32 v182, v202 offset:768
	ds_write_b32 v182, v212 offset:2048
	ds_write_b32 v182, v220 offset:2304
	ds_write_b32 v182, v230 offset:2560
	ds_write_b32 v182, v240 offset:2816
	s_or_b64 exec, exec, s[70:71]
	v_and_b32_e32 v146, -16, v156
	s_waitcnt lgkmcnt(0)
	v_or_b32_e32 v147, s34, v190
	s_waitcnt lgkmcnt(0)
	s_barrier
	v_add_u32_e32 v148, v147, v146
	s_movk_i32 s8, 0x100
	v_add_u32_e32 v146, s41, v148
	v_cmp_gt_i32_e64 s[12:13], s8, v148
	v_ashrrev_i32_e32 v147, 31, v146
	s_and_saveexec_b64 s[70:71], s[12:13]
	s_cbranch_execz .LBB0_1621
	v_lshl_add_u32 v149, v148, 4, 0
	v_add_u32_e32 v149, 0x20400, v149
	ds_read_b128 v[150:153], v149
	v_lshl_add_u64 v[154:155], v[146:147], 4, s[44:45]
	s_ashr_i32 s69, s68, 31
	v_lshl_add_u64 v[154:155], s[68:69], 2, v[154:155]
	s_waitcnt lgkmcnt(0)
	v_mov_b32_e32 v156, v151
	v_mov_b32_e32 v157, v152
	v_mov_b32_e32 v151, v153
	v_pk_add_f32 v[150:151], v[156:157], v[150:151]
	s_nop 0
	v_pk_add_f32 v[150:151], v[150:151], v[150:151] op_sel:[0,1] op_sel_hi:[1,0]
	global_store_dword v[154:155], v150, off sc1
